# cooperative LDS-DMA loaders (counted vmcnt) + conflict-free LDS swizzle in all six GEMM k-loops: FFN1, FFN2, attn-out x2, even/odd in-projection
# speedup vs baseline: 1.0284x; 1.0284x over previous
; __device__ __forceinline__ int opaque_tid() { int t = threadIdx.x; asm volatile("" : "+v"(t)); return t; }
; template <int EPI>
; __device__ __forceinline__ void gemm_tile(const Params& p, int l, const u16* __restrict__ A, int lda, const u16* __restrict__ Bt, int K, int m0, int n0, unsigned char* smem) {
;     const int tid = opaque_tid(), lane = tid & 63, wid = tid >> 6, wr = wid >> 1, wc = wid & 1, fr = lane & 15, fq = lane >> 4;
;     f32x4 acc[4][4];
; #pragma unroll
;     for (int i = 0; i < 4; ++i)
; #pragma unroll
;         for (int j = 0; j < 4; ++j) acc[i][j] = (f32x4){0.f, 0.f, 0.f, 0.f};
;     const unsigned voff = (unsigned)(lane * 16);
;     const size_t ksub = (size_t)(K >> 5) * 1024;
;     const unsigned char* Abase = (const unsigned char*)A + (size_t)(m0 >> 4) * ksub;
;     const unsigned char* Bbase = (const unsigned char*)Bt + (size_t)(n0 >> 4) * ksub;
;     (void)lda;
;     ...
;     const int nk = K >> 5;
;     G_TILE(wid, wid);
;     const unsigned char* fa = smem + (wr * 4) * 1024 + fr * 64 + fq * 16;
;     const unsigned char* fb = smem + 8192 + (wc * 4) * 1024 + fr * 64 + fq * 16;
;     int st = 0, stn = 4;
;     if (wid == 0) asm volatile("s_waitcnt vmcnt(0)" ::: "memory");
;     __builtin_amdgcn_s_barrier();
;     asm volatile("" ::: "memory");
;     for (int kt = 0; kt < nk; ++kt) {
;         if (((kt + 1) & 3) == wid && kt + 1 < nk) asm volatile("s_waitcnt vmcnt(0)" ::: "memory");
;         __builtin_amdgcn_s_barrier();
;         asm volatile("" ::: "memory");
;         if ((kt & 3) == wid && kt + 4 < nk) G_TILE(kt + 4, stn);
;         const int so = st * 16384;
;         bf16x8 af[4], bv[4];
; #pragma unroll
;         for (int i = 0; i < 4; ++i) af[i] = *(const bf16x8*)(fa + so + i * 1024);
; #pragma unroll
;         for (int j = 0; j < 4; ++j) bv[j] = *(const bf16x8*)(fb + so + j * 1024);
;         __builtin_amdgcn_s_setprio(1);
; #pragma unroll
;         for (int i = 0; i < 4; ++i)
; #pragma unroll
;             for (int j = 0; j < 4; ++j) acc[i][j] = __builtin_amdgcn_mfma_f32_16x16x32_bf16(af[i], bv[j], acc[i][j], 0, 0, 0);
;         __builtin_amdgcn_s_setprio(0);
;         st = (st == 4) ? 0 : st + 1;
;         stn = (stn == 4) ? 0 : stn + 1;
;     }
.LBB0_269:
	s_lshl_b32 s0, s40, 3
	v_mov_b32_e32 v136, v197
	s_ashr_i32 s1, s0, 31
	s_lshl_b64 s[0:1], s[0:1], 15
	v_ashrrev_i32_e32 v66, 6, v136
	v_lshlrev_b32_e32 v0, 4, v136
	v_and_b32_e32 v0, 0x3f0, v0
	s_lshl_b32 s28, s59, 3
	s_ashr_i32 s29, s28, 31
	s_lshl_b64 s[28:29], s[28:29], 15
	v_and_b32_e32 v252, 32, v136
	v_xor_b32_e32 v252, v252, v0
	v_add_u32_e32 v253, 0x8000, v252
	v_readfirstlane_b32 s36, v66
	s_add_u32 s30, s76, s0
	s_addc_u32 s31, s77, s1
	s_add_u32 s28, s16, s28
	s_addc_u32 s29, s49, s29
	s_lshl_b32 s1, s36, 16
	s_add_u32 s30, s30, s1
	s_addc_u32 s31, s31, 0
	s_add_u32 s28, s28, s1
	s_addc_u32 s29, s29, 0
	s_lshl_b32 s37, s36, 11
	s_add_i32 s38, s37, 0x2000
	s_mov_b32 s23, 0
.Loin_pro:
	s_add_i32 s1, s23, s37
	s_mov_b32 m0, s1
	s_add_i32 s1, s1, 0x400
	global_load_lds_dwordx4 v252, s[30:31]
	s_mov_b32 m0, s1
	s_add_i32 s1, s23, s38
	global_load_lds_dwordx4 v253, s[30:31]
	s_mov_b32 m0, s1
	s_add_i32 s1, s1, 0x400
	global_load_lds_dwordx4 v252, s[28:29]
	s_mov_b32 m0, s1
	s_add_u32 s30, s30, 0x400
	global_load_lds_dwordx4 v253, s[28:29]
	s_addc_u32 s31, s31, 0
	s_add_u32 s28, s28, 0x400
	s_addc_u32 s29, s29, 0
	s_add_i32 s23, s23, 0x4000
	s_cmp_lg_u32 s23, 0x10000
	s_cbranch_scc1 .Loin_pro
	v_ashrrev_i32_e32 v73, 7, v136
	v_and_b32_e32 v72, 15, v136
	v_and_b32_e32 v67, 1, v66
	v_lshlrev_b32_e32 v2, 12, v73
	v_lshlrev_b32_e32 v3, 6, v72
	v_and_b32_e32 v4, 48, v136
	v_and_b32_e32 v5, 8, v136
	v_lshlrev_b32_e32 v5, 2, v5
	v_xor_b32_e32 v4, v4, v5
	v_add3_u32 v75, v2, v3, v4
	v_lshlrev_b32_e32 v2, 12, v67
	v_add3_u32 v74, v2, v3, v4
	s_waitcnt lgkmcnt(0)
	v_mov_b32_e32 v2, 0
	v_mov_b32_e32 v3, v2
	v_mov_b32_e32 v4, v2
	v_mov_b32_e32 v5, v2
	v_mov_b32_e32 v6, v2
	v_mov_b32_e32 v7, v2
	v_mov_b32_e32 v8, v2
	v_mov_b32_e32 v9, v2
	v_mov_b32_e32 v10, v2
	v_mov_b32_e32 v11, v2
	v_mov_b32_e32 v12, v2
	v_mov_b32_e32 v13, v2
	v_mov_b32_e32 v14, v2
	v_mov_b32_e32 v15, v2
	v_mov_b32_e32 v16, v2
	v_mov_b32_e32 v17, v2
	v_mov_b32_e32 v18, v2
	v_mov_b32_e32 v19, v2
	v_mov_b32_e32 v20, v2
	v_mov_b32_e32 v21, v2
	v_mov_b32_e32 v22, v2
	v_mov_b32_e32 v23, v2
	v_mov_b32_e32 v24, v2
	v_mov_b32_e32 v25, v2
	v_mov_b32_e32 v26, v2
	v_mov_b32_e32 v27, v2
	v_mov_b32_e32 v28, v2
	v_mov_b32_e32 v29, v2
	v_mov_b32_e32 v30, v2
	v_mov_b32_e32 v31, v2
	v_mov_b32_e32 v32, v2
	v_mov_b32_e32 v33, v2
	v_mov_b32_e32 v34, v2
	v_mov_b32_e32 v35, v2
	v_mov_b32_e32 v36, v2
	v_mov_b32_e32 v37, v2
	v_mov_b32_e32 v38, v2
	v_mov_b32_e32 v39, v2
	v_mov_b32_e32 v40, v2
	v_mov_b32_e32 v41, v2
	v_mov_b32_e32 v42, v2
	v_mov_b32_e32 v43, v2
	v_mov_b32_e32 v44, v2
	v_mov_b32_e32 v45, v2
	v_mov_b32_e32 v46, v2
	v_mov_b32_e32 v47, v2
	v_mov_b32_e32 v48, v2
	v_mov_b32_e32 v49, v2
	v_mov_b32_e32 v50, v2
	v_mov_b32_e32 v51, v2
	v_mov_b32_e32 v52, v2
	v_mov_b32_e32 v53, v2
	v_mov_b32_e32 v54, v2
	v_mov_b32_e32 v55, v2
	v_mov_b32_e32 v56, v2
	v_mov_b32_e32 v57, v2
	v_mov_b32_e32 v58, v2
	v_mov_b32_e32 v59, v2
	v_mov_b32_e32 v60, v2
	v_mov_b32_e32 v61, v2
	v_mov_b32_e32 v62, v2
	v_mov_b32_e32 v63, v2
	v_mov_b32_e32 v64, v2
	v_mov_b32_e32 v65, v2
	s_mov_b64 s[46:47], 0x6adc100
	s_mov_b64 s[18:19], 0x6ae4100
	s_mov_b64 s[44:45], 0x6aec100
	s_mov_b32 s36, 0
	s_mov_b32 s0, 0
	s_branch .Loin_head
.Loin_w8:
	s_waitcnt vmcnt(8)
	s_branch .Loin_bar
.Loin_wt:
	s_cmp_eq_u32 s36, 29
	s_cbranch_scc1 .Loin_w8
	s_waitcnt vmcnt(4)
	s_branch .Loin_bar
.Loin_head:
	s_cmp_lt_u32 s36, 29
	s_cbranch_scc0 .Loin_wt
	s_waitcnt vmcnt(12)
.Loin_bar:
	s_barrier
	v_add_u32_e32 v88, s0, v75
	v_add_u32_e32 v104, s0, v74
	ds_read_b128 v[76:79], v88
	ds_read_b128 v[80:83], v88 offset:1024
	ds_read_b128 v[84:87], v88 offset:2048
	ds_read_b128 v[88:91], v88 offset:3072
	ds_read_b128 v[92:95], v104 offset:8192
	ds_read_b128 v[96:99], v104 offset:9216
	ds_read_b128 v[100:103], v104 offset:10240
	ds_read_b128 v[104:107], v104 offset:11264
	s_cmp_lt_u32 s36, 28
	s_cbranch_scc0 .Loin_mm
	s_add_i32 s1, s23, s37
	s_mov_b32 m0, s1
	s_add_i32 s1, s1, 0x400
	global_load_lds_dwordx4 v252, s[30:31]
	s_mov_b32 m0, s1
	s_add_i32 s1, s23, s38
	global_load_lds_dwordx4 v253, s[30:31]
	s_mov_b32 m0, s1
	s_add_i32 s1, s1, 0x400
	global_load_lds_dwordx4 v252, s[28:29]
	s_mov_b32 m0, s1
	s_add_u32 s30, s30, 0x400
	global_load_lds_dwordx4 v253, s[28:29]
	s_addc_u32 s31, s31, 0
	s_add_u32 s28, s28, 0x400
	s_addc_u32 s29, s29, 0
	s_add_i32 s23, s23, 0x4000
	s_cmp_eq_u32 s23, 0x14000
	s_cselect_b32 s23, 0, s23
.Loin_mm:
	s_setprio 1
	s_waitcnt lgkmcnt(0)
	v_mfma_f32_16x16x32_bf16 v[62:65], v[76:79], v[92:95], v[62:65]
	v_mfma_f32_16x16x32_bf16 v[58:61], v[76:79], v[96:99], v[58:61]
	v_mfma_f32_16x16x32_bf16 v[54:57], v[76:79], v[100:103], v[54:57]
	v_mfma_f32_16x16x32_bf16 v[50:53], v[76:79], v[104:107], v[50:53]
	v_mfma_f32_16x16x32_bf16 v[46:49], v[80:83], v[92:95], v[46:49]
	v_mfma_f32_16x16x32_bf16 v[42:45], v[80:83], v[96:99], v[42:45]
	v_mfma_f32_16x16x32_bf16 v[38:41], v[80:83], v[100:103], v[38:41]
	v_mfma_f32_16x16x32_bf16 v[34:37], v[80:83], v[104:107], v[34:37]
	v_mfma_f32_16x16x32_bf16 v[30:33], v[84:87], v[92:95], v[30:33]
	v_mfma_f32_16x16x32_bf16 v[26:29], v[84:87], v[96:99], v[26:29]
	v_mfma_f32_16x16x32_bf16 v[22:25], v[84:87], v[100:103], v[22:25]
	v_mfma_f32_16x16x32_bf16 v[18:21], v[84:87], v[104:107], v[18:21]
	v_mfma_f32_16x16x32_bf16 v[14:17], v[88:91], v[92:95], v[14:17]
	v_mfma_f32_16x16x32_bf16 v[10:13], v[88:91], v[96:99], v[10:13]
	v_mfma_f32_16x16x32_bf16 v[6:9], v[88:91], v[100:103], v[6:9]
	v_mfma_f32_16x16x32_bf16 v[2:5], v[88:91], v[104:107], v[2:5]
	s_setprio 0
	s_add_i32 s0, s0, 0x4000
	s_cmp_eq_u32 s0, 0x14000
	s_cselect_b32 s0, 0, s0
	s_add_i32 s36, s36, 1
	s_cmp_lg_u32 s36, 31
	s_cbranch_scc1 .Loin_head
	s_branch .LBB0_277
; template <int EPI, int ROWS>
; __device__ __forceinline__ void epi_process(const Params& p, int l, int m0, int n0, const float* Cs, int tid) {
;     ...
;         if (tid < 2 * ROWS) {
;             const int sl = tid / ROWS, rl = tid - sl * ROWS;
;             const int row = m0 + rl;
;             float v[64];
; #pragma unroll
;             for (int c = 0; c < 64; ++c) v[c] = Cs[rl * 129 + sl * 64 + c];
;             const int b = row / TOK, t = row - b * TOK;
;             epi_seg<EPI>(p, l, row, b, t, (n0 >> 6) + sl, v);
; template <int EPI>
; __device__ __forceinline__ void gemm_tile(const Params& p, int l, const u16* __restrict__ A, int lda, const u16* __restrict__ Bt, int K, int m0, int n0, unsigned char* smem) {
;     ...
;     for (int kt = 0; kt < nk; ++kt) {
;         if (((kt + 1) & 3) == wid && kt + 1 < nk) asm volatile("s_waitcnt vmcnt(0)" ::: "memory");
;         __builtin_amdgcn_s_barrier();
;         asm volatile("" ::: "memory");
;         if ((kt & 3) == wid && kt + 4 < nk) G_TILE(kt + 4, stn);
;         const int so = st * 16384;
;         bf16x8 af[4], bv[4];
; #pragma unroll
;         for (int i = 0; i < 4; ++i) af[i] = *(const bf16x8*)(fa + so + i * 1024);
; #pragma unroll
;         for (int j = 0; j < 4; ++j) bv[j] = *(const bf16x8*)(fb + so + j * 1024);
;         __builtin_amdgcn_s_setprio(1);
; #pragma unroll
;         for (int i = 0; i < 4; ++i)
; #pragma unroll
;             for (int j = 0; j < 4; ++j) acc[i][j] = __builtin_amdgcn_mfma_f32_16x16x32_bf16(af[i], bv[j], acc[i][j], 0, 0, 0);
;         __builtin_amdgcn_s_setprio(0);
;         st = (st == 4) ? 0 : st + 1;
;         stn = (stn == 4) ? 0 : stn + 1;
;     }
;     __syncthreads();
;     float* Cs = (float*)smem;
;     constexpr int CS = (EPI == EPI_FFN1 || EPI == EPI_Y) ? 132 : 129;
; #pragma unroll
;     for (int i = 0; i < 4; ++i)
; #pragma unroll
;         for (int j = 0; j < 4; ++j)
; #pragma unroll
;             for (int r = 0; r < 4; ++r) Cs[(wr * 64 + i * 16 + fq * 4 + r) * CS + wc * 64 + j * 16 + fr] = acc[i][j][r];
;     __syncthreads();
;     epi_process<EPI, 128>(p, l, m0, n0, Cs, tid);
.LBB0_277:
	s_waitcnt vmcnt(0)
	s_barrier
	ds_read_b128 v[68:71], v75 offset:16384
	ds_read_b128 v[76:79], v75 offset:17408
	ds_read_b128 v[80:83], v75 offset:18432
	ds_read_b128 v[84:87], v75 offset:19456
	ds_read_b128 v[88:91], v74 offset:24576
	ds_read_b128 v[92:95], v74 offset:25600
	ds_read_b128 v[96:99], v74 offset:26624
	ds_read_b128 v[100:103], v74 offset:27648
	s_setprio 1
	s_waitcnt lgkmcnt(0)
	v_mfma_f32_16x16x32_bf16 v[62:65], v[68:71], v[88:91], v[62:65]
	v_mfma_f32_16x16x32_bf16 v[58:61], v[68:71], v[92:95], v[58:61]
	v_mfma_f32_16x16x32_bf16 v[54:57], v[68:71], v[96:99], v[54:57]
	v_mfma_f32_16x16x32_bf16 v[50:53], v[68:71], v[100:103], v[50:53]
	v_mfma_f32_16x16x32_bf16 v[46:49], v[76:79], v[88:91], v[46:49]
	v_mfma_f32_16x16x32_bf16 v[42:45], v[76:79], v[92:95], v[42:45]
	v_mfma_f32_16x16x32_bf16 v[38:41], v[76:79], v[96:99], v[38:41]
	v_mfma_f32_16x16x32_bf16 v[34:37], v[76:79], v[100:103], v[34:37]
	v_mfma_f32_16x16x32_bf16 v[30:33], v[80:83], v[88:91], v[30:33]
	v_mfma_f32_16x16x32_bf16 v[26:29], v[80:83], v[92:95], v[26:29]
	v_mfma_f32_16x16x32_bf16 v[22:25], v[80:83], v[96:99], v[22:25]
	v_mfma_f32_16x16x32_bf16 v[18:21], v[80:83], v[100:103], v[18:21]
	v_mfma_f32_16x16x32_bf16 v[14:17], v[84:87], v[88:91], v[14:17]
	v_mfma_f32_16x16x32_bf16 v[10:13], v[84:87], v[92:95], v[10:13]
	v_mfma_f32_16x16x32_bf16 v[6:9], v[84:87], v[96:99], v[6:9]
	v_mfma_f32_16x16x32_bf16 v[2:5], v[84:87], v[100:103], v[2:5]
	s_setprio 0
	v_lshrrev_b32_e32 v66, 2, v136
	v_and_b32_e32 v66, 12, v66
	v_lshl_or_b32 v66, v73, 6, v66
	s_movk_i32 s0, 0x204
	v_lshl_add_u32 v67, v67, 8, 0
	v_lshlrev_b32_e32 v68, 2, v72
	v_mul_lo_u32 v66, v66, s0
	v_add3_u32 v66, v67, v68, v66
	s_waitcnt vmcnt(0)
	s_barrier
	ds_write2_b32 v66, v62, v58 offset1:16
	ds_write2_b32 v66, v63, v59 offset0:129 offset1:145
	v_add_u32_e32 v58, 0x400, v66
	ds_write2_b32 v58, v64, v60 offset0:2 offset1:18
	ds_write2_b32 v58, v65, v61 offset0:131 offset1:147
	ds_write2_b32 v66, v54, v50 offset0:32 offset1:48
	ds_write2_b32 v66, v55, v51 offset0:161 offset1:177
	ds_write2_b32 v58, v56, v52 offset0:34 offset1:50
	ds_write2_b32 v58, v57, v53 offset0:163 offset1:179
	v_add_u32_e32 v50, 0x2000, v66
	ds_write2_b32 v50, v46, v42 offset0:16 offset1:32
	ds_write2_b32 v50, v47, v43 offset0:145 offset1:161
	v_add_u32_e32 v42, 0x2400, v66
	ds_write2_b32 v42, v48, v44 offset0:18 offset1:34
	ds_write2_b32 v42, v49, v45 offset0:147 offset1:163
	ds_write2_b32 v50, v38, v34 offset0:48 offset1:64
	ds_write2_b32 v50, v39, v35 offset0:177 offset1:193
	ds_write2_b32 v42, v40, v36 offset0:50 offset1:66
	ds_write2_b32 v42, v41, v37 offset0:179 offset1:195
	v_add_u32_e32 v34, 0x4000, v66
	ds_write2_b32 v34, v30, v26 offset0:32 offset1:48
	ds_write2_b32 v34, v31, v27 offset0:161 offset1:177
	v_add_u32_e32 v26, 0x4400, v66
	ds_write2_b32 v26, v32, v28 offset0:34 offset1:50
	ds_write2_b32 v26, v33, v29 offset0:163 offset1:179
	ds_write2_b32 v34, v22, v18 offset0:64 offset1:80
	ds_write2_b32 v34, v23, v19 offset0:193 offset1:209
	ds_write2_b32 v26, v24, v20 offset0:66 offset1:82
	ds_write2_b32 v26, v25, v21 offset0:195 offset1:211
	v_add_u32_e32 v18, 0x6000, v66
	ds_write2_b32 v18, v14, v10 offset0:48 offset1:64
	ds_write2_b32 v18, v15, v11 offset0:177 offset1:193
	v_add_u32_e32 v10, 0x6400, v66
	v_cmp_gt_i32_e32 vcc, s41, v136
	ds_write2_b32 v10, v16, v12 offset0:50 offset1:66
	ds_write2_b32 v10, v17, v13 offset0:179 offset1:195
	ds_write2_b32 v18, v6, v2 offset0:80 offset1:96
	ds_write2_b32 v18, v7, v3 offset0:209 offset1:225
	ds_write2_b32 v10, v8, v4 offset0:82 offset1:98
	ds_write2_b32 v10, v9, v5 offset0:211 offset1:227
	s_waitcnt lgkmcnt(0)
	s_barrier
	s_and_saveexec_b64 s[50:51], vcc
	s_cbranch_execz .LBB0_264
	v_ashrrev_i32_e32 v2, 31, v136
	v_lshrrev_b32_e32 v2, 25, v2
	v_add_u32_e32 v2, v136, v2
	v_ashrrev_i32_e32 v3, 7, v2
	v_and_b32_e32 v2, 0xffffff80, v2
	v_sub_u32_e32 v2, v136, v2
	v_mul_lo_u32 v4, v2, s0
	v_lshlrev_b32_e32 v5, 8, v3
	v_add3_u32 v4, 0, v4, v5
	ds_read2_b32 v[86:87], v4 offset1:1
	ds_read2_b32 v[88:89], v4 offset0:2 offset1:3
	ds_read2_b32 v[90:91], v4 offset0:4 offset1:5
	ds_read2_b32 v[92:93], v4 offset0:6 offset1:7
	ds_read2_b32 v[94:95], v4 offset0:8 offset1:9
	ds_read2_b32 v[96:97], v4 offset0:10 offset1:11
	ds_read2_b32 v[16:17], v4 offset0:12 offset1:13
	ds_read2_b32 v[14:15], v4 offset0:14 offset1:15
	ds_read2_b32 v[32:33], v4 offset0:16 offset1:17
	ds_read2_b32 v[30:31], v4 offset0:18 offset1:19
	ds_read2_b32 v[28:29], v4 offset0:20 offset1:21
	ds_read2_b32 v[26:27], v4 offset0:22 offset1:23
	ds_read2_b32 v[24:25], v4 offset0:24 offset1:25
	ds_read2_b32 v[22:23], v4 offset0:26 offset1:27
	ds_read2_b32 v[20:21], v4 offset0:28 offset1:29
	ds_read2_b32 v[18:19], v4 offset0:30 offset1:31
	ds_read2_b32 v[66:67], v4 offset0:32 offset1:33
	ds_read2_b32 v[64:65], v4 offset0:34 offset1:35
	ds_read2_b32 v[62:63], v4 offset0:36 offset1:37
	ds_read2_b32 v[60:61], v4 offset0:38 offset1:39
	ds_read2_b32 v[56:57], v4 offset0:40 offset1:41
	ds_read2_b32 v[54:55], v4 offset0:42 offset1:43
	ds_read2_b32 v[52:53], v4 offset0:44 offset1:45
	ds_read2_b32 v[44:45], v4 offset0:46 offset1:47
	ds_read2_b32 v[50:51], v4 offset0:48 offset1:49
	ds_read2_b32 v[48:49], v4 offset0:50 offset1:51
	ds_read2_b32 v[46:47], v4 offset0:52 offset1:53
	ds_read2_b32 v[42:43], v4 offset0:54 offset1:55
	ds_read2_b32 v[40:41], v4 offset0:56 offset1:57
	ds_read2_b32 v[38:39], v4 offset0:58 offset1:59
	ds_read2_b32 v[36:37], v4 offset0:60 offset1:61
	ds_read2_b32 v[34:35], v4 offset0:62 offset1:63
	v_lshl_add_u32 v58, s40, 7, v2
	s_mov_b32 s0, 0x38e38e39
	v_mul_hi_i32 v2, v58, s0
	v_lshrrev_b32_e32 v4, 31, v2
	v_ashrrev_i32_e32 v2, 9, v2
	v_add_u32_e32 v138, v2, v4
	s_movk_i32 s0, 0xf700
	v_lshl_add_u32 v121, s59, 1, v3
	v_mad_i32_i24 v137, v138, s0, v58
	v_cmp_lt_i32_e32 vcc, 9, v121
	s_and_saveexec_b64 s[0:1], vcc
	s_xor_b64 s[0:1], exec, s[0:1]
	s_cbranch_execz .LBB0_296
; __device__ __forceinline__ u16 f2bf(float f) { return (u16)(pk2(f, 0.f) & 0xffffu); }
; __device__ __forceinline__ size_t vtile_off(int dv, int t, int NI) {
;     return ((size_t)(t >> 6) * (2 * NI) + (dv >> 4) * 2 + ((t >> 5) & 1)) * 512 + (dv & 15) * 32 + (t & 31);
; }
; __device__ __forceinline__ void store_v64(u16* head, int dv0, int t, int NI, const float (&v)[64]) {
; #pragma unroll
;     for (int c = 0; c < 64; ++c) head[vtile_off(dv0 + c, t, NI)] = f2bf(v[c]);
; }
	v_cmp_lt_u32_e32 vcc, 11, v121
	s_and_saveexec_b64 s[28:29], vcc
	s_xor_b64 s[36:37], exec, s[28:29]
	s_cbranch_execz .LBB0_293
	v_cmp_lt_u32_e32 vcc, 19, v121
	s_and_saveexec_b64 s[28:29], vcc
	s_xor_b64 s[38:39], exec, s[28:29]
	s_cbranch_execz .LBB0_288
	v_cmp_lt_u32_e32 vcc, 27, v121
	s_and_saveexec_b64 s[28:29], vcc
	s_xor_b64 s[28:29], exec, s[28:29]
	s_cbranch_execz .LBB0_283
	v_subrev_u32_e32 v0, 28, v121
	v_readlane_b32 s18, v250, 4
	v_lshrrev_b32_e32 v0, 1, v0
	v_readlane_b32 s19, v250, 5
	v_ashrrev_i32_e32 v4, 6, v137
	v_lshl_add_u32 v0, v138, 2, v0
	v_mov_b64_e32 v[2:3], s[18:19]
	s_mov_b32 s23, 0x90000
	v_ashrrev_i32_e32 v5, 31, v4
	v_lshlrev_b32_e32 v6, 3, v121
	v_mad_i64_i32 v[2:3], s[30:31], v0, s23, v[2:3]
	v_lshlrev_b64 v[4:5], 4, v[4:5]
	v_bfe_u32 v0, v136, 5, 1
	v_and_b32_e32 v6, 8, v6
	v_or3_b32 v4, v4, v0, v6
	v_and_b32_e32 v8, 31, v136
	v_lshlrev_b64 v[6:7], 10, v[4:5]
	v_lshl_add_u64 v[6:7], v[2:3], 0, v[6:7]
	v_lshlrev_b32_e32 v0, 1, v8
	v_lshl_add_u64 v[6:7], v[6:7], 0, v[0:1]
	s_waitcnt lgkmcnt(14)
	v_cvt_pk_bf16_f32 v8, v87, s0
	global_store_short v[6:7], v8, off offset:64
	v_cvt_pk_bf16_f32 v8, v88, s0
	global_store_short v[6:7], v8, off offset:128
	v_cvt_pk_bf16_f32 v8, v89, s0
	global_store_short v[6:7], v8, off offset:192
	v_cvt_pk_bf16_f32 v8, v90, s0
	global_store_short v[6:7], v8, off offset:256
	v_cvt_pk_bf16_f32 v8, v91, s0
	global_store_short v[6:7], v8, off offset:320
	v_cvt_pk_bf16_f32 v8, v92, s0
	global_store_short v[6:7], v8, off offset:384
	v_cvt_pk_bf16_f32 v8, v93, s0
	global_store_short v[6:7], v8, off offset:448
	v_cvt_pk_bf16_f32 v8, v94, s0
	global_store_short v[6:7], v8, off offset:512
	v_cvt_pk_bf16_f32 v8, v95, s0
	global_store_short v[6:7], v8, off offset:576
	v_cvt_pk_bf16_f32 v8, v96, s0
	global_store_short v[6:7], v8, off offset:640
	v_cvt_pk_bf16_f32 v8, v97, s0
	global_store_short v[6:7], v8, off offset:704
	v_cvt_pk_bf16_f32 v8, v16, s0
	global_store_short v[6:7], v8, off offset:768
	v_cvt_pk_bf16_f32 v8, v17, s0
	global_store_short v[6:7], v8, off offset:832
	v_cvt_pk_bf16_f32 v8, v14, s0
	v_cvt_pk_bf16_f32 v9, v86, s0
	global_store_short v[6:7], v8, off offset:896
	v_cvt_pk_bf16_f32 v8, v15, s0
	global_store_short v[6:7], v9, off
	global_store_short v[6:7], v8, off offset:960
	v_or_b32_e32 v6, 2, v4
	v_mov_b32_e32 v7, v5
	v_lshlrev_b64 v[6:7], 10, v[6:7]
	v_lshl_add_u64 v[6:7], v[2:3], 0, v[6:7]
	v_cvt_pk_bf16_f32 v8, v32, s0
	v_lshl_add_u64 v[6:7], v[6:7], 0, v[0:1]
	global_store_short v[6:7], v8, off
	v_cvt_pk_bf16_f32 v8, v33, s0
	global_store_short v[6:7], v8, off offset:64
	v_cvt_pk_bf16_f32 v8, v30, s0
	global_store_short v[6:7], v8, off offset:128
	v_cvt_pk_bf16_f32 v8, v31, s0
	global_store_short v[6:7], v8, off offset:192
	v_cvt_pk_bf16_f32 v8, v28, s0
	global_store_short v[6:7], v8, off offset:256
	v_cvt_pk_bf16_f32 v8, v29, s0
	global_store_short v[6:7], v8, off offset:320
	v_cvt_pk_bf16_f32 v8, v26, s0
	global_store_short v[6:7], v8, off offset:384
	v_cvt_pk_bf16_f32 v8, v27, s0
	global_store_short v[6:7], v8, off offset:448
	v_cvt_pk_bf16_f32 v8, v24, s0
	global_store_short v[6:7], v8, off offset:512
	v_cvt_pk_bf16_f32 v8, v25, s0
	global_store_short v[6:7], v8, off offset:576
	v_cvt_pk_bf16_f32 v8, v22, s0
	global_store_short v[6:7], v8, off offset:640
	v_cvt_pk_bf16_f32 v8, v23, s0
	global_store_short v[6:7], v8, off offset:704
	v_cvt_pk_bf16_f32 v8, v20, s0
	global_store_short v[6:7], v8, off offset:768
	v_cvt_pk_bf16_f32 v8, v21, s0
	global_store_short v[6:7], v8, off offset:832
	v_cvt_pk_bf16_f32 v8, v18, s0
	global_store_short v[6:7], v8, off offset:896
	v_cvt_pk_bf16_f32 v8, v19, s0
	global_store_short v[6:7], v8, off offset:960
	v_or_b32_e32 v6, 4, v4
	v_mov_b32_e32 v7, v5
	v_lshlrev_b64 v[6:7], 10, v[6:7]
	v_lshl_add_u64 v[6:7], v[2:3], 0, v[6:7]
	v_or_b32_e32 v4, 6, v4
	v_cvt_pk_bf16_f32 v8, v66, s0
	v_lshl_add_u64 v[6:7], v[6:7], 0, v[0:1]
	v_lshlrev_b64 v[4:5], 10, v[4:5]
	global_store_short v[6:7], v8, off
	v_cvt_pk_bf16_f32 v8, v67, s0
	v_lshl_add_u64 v[2:3], v[2:3], 0, v[4:5]
	global_store_short v[6:7], v8, off offset:64
	v_cvt_pk_bf16_f32 v8, v64, s0
	v_lshl_add_u64 v[2:3], v[2:3], 0, v[0:1]
	s_waitcnt lgkmcnt(7)
	v_cvt_pk_bf16_f32 v0, v51, s0
	global_store_short v[6:7], v8, off offset:128
	v_cvt_pk_bf16_f32 v8, v65, s0
	global_store_short v[2:3], v0, off offset:64
	s_waitcnt lgkmcnt(6)
	v_cvt_pk_bf16_f32 v0, v48, s0
	global_store_short v[6:7], v8, off offset:192
	v_cvt_pk_bf16_f32 v8, v62, s0
	global_store_short v[2:3], v0, off offset:128
	v_cvt_pk_bf16_f32 v0, v49, s0
	global_store_short v[6:7], v8, off offset:256
	v_cvt_pk_bf16_f32 v8, v63, s0
	global_store_short v[2:3], v0, off offset:192
	s_waitcnt lgkmcnt(5)
	v_cvt_pk_bf16_f32 v0, v46, s0
	global_store_short v[6:7], v8, off offset:320
	v_cvt_pk_bf16_f32 v8, v60, s0
	global_store_short v[2:3], v0, off offset:256
	v_cvt_pk_bf16_f32 v0, v47, s0
	global_store_short v[6:7], v8, off offset:384
	v_cvt_pk_bf16_f32 v8, v61, s0
	global_store_short v[2:3], v0, off offset:320
	s_waitcnt lgkmcnt(4)
	v_cvt_pk_bf16_f32 v0, v42, s0
	global_store_short v[6:7], v8, off offset:448
	v_cvt_pk_bf16_f32 v8, v56, s0
	global_store_short v[2:3], v0, off offset:384
	v_cvt_pk_bf16_f32 v0, v43, s0
	global_store_short v[6:7], v8, off offset:512
	v_cvt_pk_bf16_f32 v8, v57, s0
	global_store_short v[2:3], v0, off offset:448
	s_waitcnt lgkmcnt(3)
	v_cvt_pk_bf16_f32 v0, v40, s0
	global_store_short v[6:7], v8, off offset:576
	v_cvt_pk_bf16_f32 v8, v54, s0
	global_store_short v[2:3], v0, off offset:512
	v_cvt_pk_bf16_f32 v0, v41, s0
	global_store_short v[6:7], v8, off offset:640
	v_cvt_pk_bf16_f32 v8, v55, s0
	global_store_short v[2:3], v0, off offset:576
	s_waitcnt lgkmcnt(2)
	v_cvt_pk_bf16_f32 v0, v38, s0
	global_store_short v[6:7], v8, off offset:704
	v_cvt_pk_bf16_f32 v8, v52, s0
	global_store_short v[2:3], v0, off offset:640
	v_cvt_pk_bf16_f32 v0, v39, s0
	global_store_short v[6:7], v8, off offset:768
	v_cvt_pk_bf16_f32 v8, v53, s0
	global_store_short v[2:3], v0, off offset:704
	s_waitcnt lgkmcnt(1)
	v_cvt_pk_bf16_f32 v0, v36, s0
	global_store_short v[6:7], v8, off offset:832
	v_cvt_pk_bf16_f32 v8, v44, s0
	global_store_short v[2:3], v0, off offset:768
	v_cvt_pk_bf16_f32 v0, v37, s0
	global_store_short v[6:7], v8, off offset:896
	v_cvt_pk_bf16_f32 v8, v45, s0
	global_store_short v[2:3], v0, off offset:832
	s_waitcnt lgkmcnt(0)
	v_cvt_pk_bf16_f32 v0, v34, s0
	global_store_short v[6:7], v8, off offset:960
	v_cvt_pk_bf16_f32 v6, v50, s0
	global_store_short v[2:3], v0, off offset:896
	v_cvt_pk_bf16_f32 v0, v35, s0
	global_store_short v[2:3], v6, off
	global_store_short v[2:3], v0, off offset:960

; __device__ __forceinline__ int opaque_tid() { int t = threadIdx.x; asm volatile("" : "+v"(t)); return t; }
; #define G3_TILE(kt_, st_) do { const size_t ko_ = (size_t)(kt_) * 1024; unsigned char* d_ = smem + (st_) * 20480; \
;         _Pragma("unroll") for (int s_ = 0; s_ < 12; ++s_) GLDS16(Abase + (size_t)s_ * ksub + ko_ + voff, d_ + s_ * 1024); \
;         _Pragma("unroll") for (int s_ = 0; s_ < 8; ++s_) GLDS16(Bbase + (size_t)s_ * ksub + ko_ + voff, d_ + 12288 + s_ * 1024); } while (0)
; template <int EPI>
; __device__ __forceinline__ void gemm_tile3(const Params& p, int l, const u16* __restrict__ A, int lda, const u16* __restrict__ Bt, int K, int m0, int n0, unsigned char* smem) {
;     const int tid = opaque_tid(), lane = tid & 63, wid = tid >> 6, wr = wid >> 1, wc = wid & 1, fr = lane & 15, fq = lane >> 4;
;     f32x4 acc[6][4];
; #pragma unroll
;     for (int i = 0; i < 6; ++i)
; #pragma unroll
;         for (int j = 0; j < 4; ++j) acc[i][j] = (f32x4){0.f, 0.f, 0.f, 0.f};
;     const unsigned voff = (unsigned)(lane * 16);
;     const size_t ksub = (size_t)(K >> 5) * 1024;
;     const unsigned char* Abase = (const unsigned char*)A + (size_t)(m0 >> 4) * ksub;
;     const unsigned char* Bbase = (const unsigned char*)Bt + (size_t)(n0 >> 4) * ksub;
;     (void)lda;
;     ...
;     const int nk = K >> 5;
;     if (wid < 3) G3_TILE(wid, wid);
;     const unsigned char* fa = smem + (wr * 6) * 1024 + fr * 64 + fq * 16;
;     const unsigned char* fb = smem + 12288 + (wc * 4) * 1024 + fr * 64 + fq * 16;
;     int st = 0, stn = 3;
;     if (wid == 0) asm volatile("s_waitcnt vmcnt(0)" ::: "memory");
;     asm volatile("s_waitcnt lgkmcnt(0)" ::: "memory");
;     __builtin_amdgcn_s_barrier();
;     asm volatile("" ::: "memory");
.LBB0_454:
	s_lshl_b32 s16, s16, 7
	s_lshl_b32 s0, s0, 4
	s_sub_i32 s0, s0, s16
	s_and_b32 s0, s0, 0xffffff80
	s_mulk_i32 s1, 0xc0
	v_mov_b32_e32 v104, v197
	s_ashr_i32 s30, s0, 4
	s_lshr_b32 s84, s1, 4
	v_ashrrev_i32_e32 v98, 6, v104
	v_lshlrev_b32_e32 v0, 4, v104
	s_ashr_i32 s31, s30, 31
	v_and_b32_e32 v0, 0x3f0, v0
	s_lshl_b64 s[28:29], s[84:85], 15
	s_lshl_b64 s[30:31], s[30:31], 15
	v_and_b32_e32 v252, 32, v104
	v_xor_b32_e32 v252, v252, v0
	v_add_u32_e32 v253, 0x8000, v252
	v_add_u32_e32 v254, 0x10000, v252
	v_readfirstlane_b32 s36, v98
	s_add_u32 s28, s76, s28
	s_addc_u32 s29, s77, s29
	s_add_u32 s30, s39, s30
	s_addc_u32 s31, s40, s31
	s_mul_i32 s17, s36, 0x18000
	s_add_u32 s28, s28, s17
	s_addc_u32 s29, s29, 0
	s_lshl_b32 s17, s36, 16
	s_add_u32 s30, s30, s17
	s_addc_u32 s31, s31, 0
	s_mul_i32 s54, s36, 0xc00
	s_lshl_b32 s55, s36, 11
	s_addk_i32 s55, 0x3000
	s_mov_b32 s16, 0
.LoA_pro:
	s_add_i32 s17, s16, s54
	s_add_i32 s18, s16, s55
	s_mov_b32 m0, s17
	s_add_i32 s17, s17, 0x400
	global_load_lds_dwordx4 v252, s[28:29]
	s_mov_b32 m0, s17
	s_add_i32 s17, s17, 0x400
	global_load_lds_dwordx4 v253, s[28:29]
	s_mov_b32 m0, s17
	s_nop 0
	global_load_lds_dwordx4 v254, s[28:29]
	s_mov_b32 m0, s18
	s_add_i32 s18, s18, 0x400
	global_load_lds_dwordx4 v252, s[30:31]
	s_mov_b32 m0, s18
	s_add_u32 s28, s28, 0x400
	global_load_lds_dwordx4 v253, s[30:31]
	s_addc_u32 s29, s29, 0
	s_add_u32 s30, s30, 0x400
	s_addc_u32 s31, s31, 0
	s_add_i32 s16, s16, 0x5000
	s_cmp_lg_u32 s16, 0xf000
	s_cbranch_scc1 .LoA_pro
	v_ashrrev_i32_e32 v105, 7, v104
	s_movk_i32 s17, 0x1800
	v_and_b32_e32 v106, 15, v104
	v_mul_lo_u32 v2, v105, s17
	v_and_b32_e32 v99, 1, v98
	v_lshlrev_b32_e32 v3, 6, v106
	v_and_b32_e32 v4, 48, v104
	v_and_b32_e32 v5, 8, v104
	v_lshlrev_b32_e32 v5, 2, v5
	v_xor_b32_e32 v4, v4, v5
	v_add3_u32 v107, v2, v3, v4
	v_lshlrev_b32_e32 v2, 12, v99
	v_add3_u32 v108, v2, v3, v4
	s_waitcnt lgkmcnt(0)
	v_mov_b32_e32 v2, 0
	v_mov_b32_e32 v3, v2
	v_mov_b32_e32 v4, v2
	v_mov_b32_e32 v5, v2
	v_mov_b32_e32 v6, v2
	v_mov_b32_e32 v7, v2
	v_mov_b32_e32 v8, v2
	v_mov_b32_e32 v9, v2
	v_mov_b32_e32 v10, v2
	v_mov_b32_e32 v11, v2
	v_mov_b32_e32 v12, v2
	v_mov_b32_e32 v13, v2
	v_mov_b32_e32 v14, v2
	v_mov_b32_e32 v15, v2
	v_mov_b32_e32 v16, v2
	v_mov_b32_e32 v17, v2
	v_mov_b32_e32 v18, v2
	v_mov_b32_e32 v19, v2
	v_mov_b32_e32 v20, v2
	v_mov_b32_e32 v21, v2
	v_mov_b32_e32 v22, v2
	v_mov_b32_e32 v23, v2
	v_mov_b32_e32 v24, v2
	v_mov_b32_e32 v25, v2
	v_mov_b32_e32 v26, v2
	v_mov_b32_e32 v27, v2
	v_mov_b32_e32 v28, v2
	v_mov_b32_e32 v29, v2
	v_mov_b32_e32 v30, v2
	v_mov_b32_e32 v31, v2
	v_mov_b32_e32 v32, v2
	v_mov_b32_e32 v33, v2
	v_mov_b32_e32 v34, v2
	v_mov_b32_e32 v35, v2
	v_mov_b32_e32 v36, v2
	v_mov_b32_e32 v37, v2
	v_mov_b32_e32 v38, v2
	v_mov_b32_e32 v39, v2
	v_mov_b32_e32 v40, v2
	v_mov_b32_e32 v41, v2
	v_mov_b32_e32 v42, v2
	v_mov_b32_e32 v43, v2
	v_mov_b32_e32 v44, v2
	v_mov_b32_e32 v45, v2
	v_mov_b32_e32 v46, v2
	v_mov_b32_e32 v47, v2
	v_mov_b32_e32 v48, v2
	v_mov_b32_e32 v49, v2
	v_mov_b32_e32 v50, v2
	v_mov_b32_e32 v51, v2
	v_mov_b32_e32 v52, v2
	v_mov_b32_e32 v53, v2
	v_mov_b32_e32 v54, v2
	v_mov_b32_e32 v55, v2
	v_mov_b32_e32 v56, v2
	v_mov_b32_e32 v57, v2
	v_mov_b32_e32 v58, v2
	v_mov_b32_e32 v59, v2
	v_mov_b32_e32 v60, v2
	v_mov_b32_e32 v61, v2
	v_mov_b32_e32 v62, v2
	v_mov_b32_e32 v63, v2
	v_mov_b32_e32 v64, v2
	v_mov_b32_e32 v65, v2
	v_mov_b32_e32 v66, v2
	v_mov_b32_e32 v67, v2
	v_mov_b32_e32 v68, v2
	v_mov_b32_e32 v69, v2
	v_mov_b32_e32 v70, v2
	v_mov_b32_e32 v71, v2
	v_mov_b32_e32 v72, v2
	v_mov_b32_e32 v73, v2
	v_mov_b32_e32 v74, v2
	v_mov_b32_e32 v75, v2
	v_mov_b32_e32 v76, v2
	v_mov_b32_e32 v77, v2
	v_mov_b32_e32 v78, v2
	v_mov_b32_e32 v79, v2
	v_mov_b32_e32 v80, v2
	v_mov_b32_e32 v81, v2
	v_mov_b32_e32 v82, v2
	v_mov_b32_e32 v83, v2
	v_mov_b32_e32 v84, v2
	v_mov_b32_e32 v85, v2
	v_mov_b32_e32 v86, v2
	v_mov_b32_e32 v87, v2
	v_mov_b32_e32 v88, v2
	v_mov_b32_e32 v89, v2
	v_mov_b32_e32 v90, v2
	v_mov_b32_e32 v91, v2
	v_mov_b32_e32 v92, v2
	v_mov_b32_e32 v93, v2
	v_mov_b32_e32 v94, v2
	v_mov_b32_e32 v95, v2
	v_mov_b32_e32 v96, v2
	v_mov_b32_e32 v97, v2
	s_mov_b32 s37, 0
	s_mov_b32 s23, 0
	s_branch .LoA_head
; template <int EPI>
; __device__ __forceinline__ void gemm_tile3(const Params& p, int l, const u16* __restrict__ A, int lda, const u16* __restrict__ Bt, int K, int m0, int n0, unsigned char* smem) {
;     ...
;     for (int kt = 0; kt < nk; ++kt) {
;         if (((kt + 1) & 3) == wid && kt + 1 < nk) asm volatile("s_waitcnt vmcnt(0)" ::: "memory");
;         __builtin_amdgcn_s_barrier();
;         asm volatile("" ::: "memory");
;         if (((kt + 3) & 3) == wid && kt + 3 < nk) G3_TILE(kt + 3, stn);
;         const int so = st * 20480;
;         bf16x8 af[6], bv[4];
;         {
;             typedef __attribute__((address_space(3))) unsigned char lds_u8;
;             const unsigned la = (unsigned)(uintptr_t)(lds_u8*)(fa + so);
;             const unsigned lb = (unsigned)(uintptr_t)(lds_u8*)(fb + so);
;     ...
;             DSR128(bv[0], lb, 0); DSR128(bv[1], lb, 1024); DSR128(bv[2], lb, 2048); DSR128(bv[3], lb, 3072);
;             DSR128(af[0], la, 0); DSR128(af[1], la, 1024); DSR128(af[2], la, 2048); DSR128(af[3], la, 3072); DSR128(af[4], la, 4096); DSR128(af[5], la, 5120);
;         }
;         __builtin_amdgcn_sched_barrier(0);
;         asm volatile("s_waitcnt lgkmcnt(5)" : "+v"(bv[0]), "+v"(bv[1]), "+v"(bv[2]), "+v"(bv[3]), "+v"(af[0]));
;         __builtin_amdgcn_sched_barrier(0);
; #pragma unroll
;         for (int j = 0; j < 4; ++j) acc[0][j] = __builtin_amdgcn_mfma_f32_16x16x32_bf16(bv[j], af[0], acc[0][j], 0, 0, 0);
;         __builtin_amdgcn_sched_barrier(0);
;         asm volatile("s_waitcnt lgkmcnt(4)" : "+v"(af[1]));
;         __builtin_amdgcn_sched_barrier(0);
; #pragma unroll
;         for (int j = 0; j < 4; ++j) acc[1][j] = __builtin_amdgcn_mfma_f32_16x16x32_bf16(bv[j], af[1], acc[1][j], 0, 0, 0);
;         __builtin_amdgcn_sched_barrier(0);
;         asm volatile("s_waitcnt lgkmcnt(3)" : "+v"(af[2]));
;         __builtin_amdgcn_sched_barrier(0);
; #pragma unroll
;         for (int j = 0; j < 4; ++j) acc[2][j] = __builtin_amdgcn_mfma_f32_16x16x32_bf16(bv[j], af[2], acc[2][j], 0, 0, 0);
;         __builtin_amdgcn_sched_barrier(0);
;         asm volatile("s_waitcnt lgkmcnt(2)" : "+v"(af[3]));
;         __builtin_amdgcn_sched_barrier(0);
; #pragma unroll
;         for (int j = 0; j < 4; ++j) acc[3][j] = __builtin_amdgcn_mfma_f32_16x16x32_bf16(bv[j], af[3], acc[3][j], 0, 0, 0);
;         __builtin_amdgcn_sched_barrier(0);
.LoA_wt:
	s_cmp_eq_u32 s37, 30
	s_cbranch_scc0 .LoA_w0
	s_waitcnt vmcnt(5)
	s_branch .LoA_bar
.LoA_w0:
	s_waitcnt vmcnt(0)
	s_branch .LoA_bar
.LoA_head:
	s_cmp_lt_u32 s37, 30
	s_cbranch_scc0 .LoA_wt
	s_waitcnt vmcnt(10)
.LoA_bar:
	s_barrier
	v_add_u32_e32 v109, s23, v108
	v_add_u32_e32 v0, s23, v107
	v_add_u32_e32 v109, 0x3000, v109
	ds_read_b128 v[110:113], v109 offset:0
	ds_read_b128 v[114:117], v109 offset:1024
	ds_read_b128 v[118:121], v109 offset:2048
	ds_read_b128 v[122:125], v109 offset:3072
	ds_read_b128 v[126:129], v0 offset:0
	ds_read_b128 v[130:133], v0 offset:1024
	ds_read_b128 v[134:137], v0 offset:2048
	ds_read_b128 v[138:141], v0 offset:3072
	ds_read_b128 v[142:145], v0 offset:4096
	ds_read_b128 v[146:149], v0 offset:5120
	s_cmp_lt_u32 s37, 29
	s_cbranch_scc0 .LoA_mm
	s_add_i32 s17, s16, s54
	s_add_i32 s18, s16, s55
	s_mov_b32 m0, s17
	s_add_i32 s17, s17, 0x400
	global_load_lds_dwordx4 v252, s[28:29]
	s_mov_b32 m0, s17
	s_add_i32 s17, s17, 0x400
	global_load_lds_dwordx4 v253, s[28:29]
	s_mov_b32 m0, s17
	s_nop 0
	global_load_lds_dwordx4 v254, s[28:29]
	s_mov_b32 m0, s18
	s_add_i32 s18, s18, 0x400
	global_load_lds_dwordx4 v252, s[30:31]
	s_mov_b32 m0, s18
	s_add_u32 s28, s28, 0x400
	global_load_lds_dwordx4 v253, s[30:31]
	s_addc_u32 s29, s29, 0
	s_add_u32 s30, s30, 0x400
	s_addc_u32 s31, s31, 0
	s_add_i32 s16, s16, 0x5000
	s_cmp_eq_u32 s16, 0x14000
	s_cselect_b32 s16, 0, s16
.LoA_mm:
	s_waitcnt lgkmcnt(5)
	s_nop 0
	v_mfma_f32_16x16x32_bf16 v[94:97], v[110:113], v[126:129], v[94:97]
	v_mfma_f32_16x16x32_bf16 v[90:93], v[114:117], v[126:129], v[90:93]
	v_mfma_f32_16x16x32_bf16 v[86:89], v[118:121], v[126:129], v[86:89]
	v_mfma_f32_16x16x32_bf16 v[82:85], v[122:125], v[126:129], v[82:85]
	s_waitcnt lgkmcnt(4)
	s_nop 0
	v_mfma_f32_16x16x32_bf16 v[78:81], v[110:113], v[130:133], v[78:81]
	v_mfma_f32_16x16x32_bf16 v[74:77], v[114:117], v[130:133], v[74:77]
	v_mfma_f32_16x16x32_bf16 v[70:73], v[118:121], v[130:133], v[70:73]
	v_mfma_f32_16x16x32_bf16 v[66:69], v[122:125], v[130:133], v[66:69]
	s_waitcnt lgkmcnt(3)
	s_nop 0
	v_mfma_f32_16x16x32_bf16 v[62:65], v[110:113], v[134:137], v[62:65]
	v_mfma_f32_16x16x32_bf16 v[58:61], v[114:117], v[134:137], v[58:61]
	v_mfma_f32_16x16x32_bf16 v[54:57], v[118:121], v[134:137], v[54:57]
	v_mfma_f32_16x16x32_bf16 v[50:53], v[122:125], v[134:137], v[50:53]
	s_waitcnt lgkmcnt(2)
	s_nop 0
	v_mfma_f32_16x16x32_bf16 v[46:49], v[110:113], v[138:141], v[46:49]
	v_mfma_f32_16x16x32_bf16 v[42:45], v[114:117], v[138:141], v[42:45]
	v_mfma_f32_16x16x32_bf16 v[38:41], v[118:121], v[138:141], v[38:41]
	v_mfma_f32_16x16x32_bf16 v[34:37], v[122:125], v[138:141], v[34:37]
	s_waitcnt lgkmcnt(1)
	s_nop 0
	v_mfma_f32_16x16x32_bf16 v[30:33], v[110:113], v[142:145], v[30:33]
	v_mfma_f32_16x16x32_bf16 v[26:29], v[114:117], v[142:145], v[26:29]
	v_mfma_f32_16x16x32_bf16 v[22:25], v[118:121], v[142:145], v[22:25]
	v_mfma_f32_16x16x32_bf16 v[18:21], v[122:125], v[142:145], v[18:21]
	s_waitcnt lgkmcnt(0)
	s_add_i32 s23, s23, 0x5000
	s_add_i32 s37, s37, 1
	v_mfma_f32_16x16x32_bf16 v[14:17], v[110:113], v[146:149], v[14:17]
	s_cmp_eq_u32 s23, 0x14000
	s_cselect_b32 s23, 0, s23
	v_mfma_f32_16x16x32_bf16 v[10:13], v[114:117], v[146:149], v[10:13]
	s_cmp_lg_u32 s37, 32
	v_mfma_f32_16x16x32_bf16 v[6:9], v[118:121], v[146:149], v[6:9]
	v_mfma_f32_16x16x32_bf16 v[2:5], v[122:125], v[146:149], v[2:5]
	s_cbranch_scc1 .LoA_head
	s_branch .LBB0_451

; __device__ __forceinline__ int opaque_tid() { int t = threadIdx.x; asm volatile("" : "+v"(t)); return t; }
; #define G_TILE(kt_, st_) do { const size_t ko_ = (size_t)(kt_) * 1024; unsigned char* d_ = smem + (st_) * 16384; \
;         _Pragma("unroll") for (int s_ = 0; s_ < 8; ++s_) GLDS16(Abase + (size_t)s_ * ksub + ko_ + voff, d_ + s_ * 1024); \
;         _Pragma("unroll") for (int s_ = 0; s_ < 8; ++s_) GLDS16(Bbase + (size_t)s_ * ksub + ko_ + voff, d_ + 8192 + s_ * 1024); } while (0)
; template <int EPI>
; __device__ __forceinline__ void gemm_tile(const Params& p, int l, const u16* __restrict__ A, int lda, const u16* __restrict__ Bt, int K, int m0, int n0, unsigned char* smem) {
;     const int tid = opaque_tid(), lane = tid & 63, wid = tid >> 6, wr = wid >> 1, wc = wid & 1, fr = lane & 15, fq = lane >> 4;
;     f32x4 acc[4][4];
; #pragma unroll
;     for (int i = 0; i < 4; ++i)
; #pragma unroll
;         for (int j = 0; j < 4; ++j) acc[i][j] = (f32x4){0.f, 0.f, 0.f, 0.f};
;     const unsigned voff = (unsigned)(lane * 16);
;     const size_t ksub = (size_t)(K >> 5) * 1024;
;     const unsigned char* Abase = (const unsigned char*)A + (size_t)(m0 >> 4) * ksub;
;     const unsigned char* Bbase = (const unsigned char*)Bt + (size_t)(n0 >> 4) * ksub;
;     (void)lda;
;     ...
;     const int nk = K >> 5;
;     G_TILE(wid, wid);
;     const unsigned char* fa = smem + (wr * 4) * 1024 + fr * 64 + fq * 16;
;     const unsigned char* fb = smem + 8192 + (wc * 4) * 1024 + fr * 64 + fq * 16;
;     int st = 0, stn = 4;
;     if (wid == 0) asm volatile("s_waitcnt vmcnt(0)" ::: "memory");
;     __builtin_amdgcn_s_barrier();
;     asm volatile("" ::: "memory");
.LBB0_473:
	s_lshl_b32 s0, s50, 3
	v_mov_b32_e32 v110, v197
	s_ashr_i32 s1, s0, 31
	s_lshl_b64 s[0:1], s[0:1], 15
	v_ashrrev_i32_e32 v66, 6, v110
	v_lshlrev_b32_e32 v0, 4, v110
	v_and_b32_e32 v0, 0x3f0, v0
	s_lshl_b32 s28, s59, 3
	s_ashr_i32 s29, s28, 31
	s_lshl_b64 s[28:29], s[28:29], 15
	v_and_b32_e32 v252, 32, v110
	v_xor_b32_e32 v252, v252, v0
	v_add_u32_e32 v253, 0x8000, v252
	v_readfirstlane_b32 s36, v66
	s_add_u32 s30, s76, s0
	s_addc_u32 s31, s77, s1
	s_add_u32 s28, s16, s28
	s_addc_u32 s29, s49, s29
	s_lshl_b32 s1, s36, 16
	s_add_u32 s30, s30, s1
	s_addc_u32 s31, s31, 0
	s_add_u32 s28, s28, s1
	s_addc_u32 s29, s29, 0
	s_lshl_b32 s37, s36, 11
	s_add_i32 s38, s37, 0x2000
	s_mov_b32 s23, 0
.Lein_pro:
	s_add_i32 s1, s23, s37
	s_mov_b32 m0, s1
	s_add_i32 s1, s1, 0x400
	global_load_lds_dwordx4 v252, s[30:31]
	s_mov_b32 m0, s1
	s_add_i32 s1, s23, s38
	global_load_lds_dwordx4 v253, s[30:31]
	s_mov_b32 m0, s1
	s_add_i32 s1, s1, 0x400
	global_load_lds_dwordx4 v252, s[28:29]
	s_mov_b32 m0, s1
	s_add_u32 s30, s30, 0x400
	global_load_lds_dwordx4 v253, s[28:29]
	s_addc_u32 s31, s31, 0
	s_add_u32 s28, s28, 0x400
	s_addc_u32 s29, s29, 0
	s_add_i32 s23, s23, 0x4000
	s_cmp_lg_u32 s23, 0x10000
	s_cbranch_scc1 .Lein_pro
	v_ashrrev_i32_e32 v73, 7, v110
	v_and_b32_e32 v72, 15, v110
	v_and_b32_e32 v67, 1, v66
	v_lshlrev_b32_e32 v2, 12, v73
	v_lshlrev_b32_e32 v3, 6, v72
	v_and_b32_e32 v4, 48, v110
	v_and_b32_e32 v5, 8, v110
	v_lshlrev_b32_e32 v5, 2, v5
	v_xor_b32_e32 v4, v4, v5
	v_add3_u32 v75, v2, v3, v4
	v_lshlrev_b32_e32 v2, 12, v67
	v_add3_u32 v74, v2, v3, v4
	s_waitcnt lgkmcnt(0)
	v_mov_b32_e32 v2, 0
	v_mov_b32_e32 v3, v2
	v_mov_b32_e32 v4, v2
	v_mov_b32_e32 v5, v2
	v_mov_b32_e32 v6, v2
	v_mov_b32_e32 v7, v2
	v_mov_b32_e32 v8, v2
	v_mov_b32_e32 v9, v2
	v_mov_b32_e32 v10, v2
	v_mov_b32_e32 v11, v2
	v_mov_b32_e32 v12, v2
	v_mov_b32_e32 v13, v2
	v_mov_b32_e32 v14, v2
	v_mov_b32_e32 v15, v2
	v_mov_b32_e32 v16, v2
	v_mov_b32_e32 v17, v2
	v_mov_b32_e32 v18, v2
	v_mov_b32_e32 v19, v2
	v_mov_b32_e32 v20, v2
	v_mov_b32_e32 v21, v2
	v_mov_b32_e32 v22, v2
	v_mov_b32_e32 v23, v2
	v_mov_b32_e32 v24, v2
	v_mov_b32_e32 v25, v2
	v_mov_b32_e32 v26, v2
	v_mov_b32_e32 v27, v2
	v_mov_b32_e32 v28, v2
	v_mov_b32_e32 v29, v2
	v_mov_b32_e32 v30, v2
	v_mov_b32_e32 v31, v2
	v_mov_b32_e32 v32, v2
	v_mov_b32_e32 v33, v2
	v_mov_b32_e32 v34, v2
	v_mov_b32_e32 v35, v2
	v_mov_b32_e32 v36, v2
	v_mov_b32_e32 v37, v2
	v_mov_b32_e32 v38, v2
	v_mov_b32_e32 v39, v2
	v_mov_b32_e32 v40, v2
	v_mov_b32_e32 v41, v2
	v_mov_b32_e32 v42, v2
	v_mov_b32_e32 v43, v2
	v_mov_b32_e32 v44, v2
	v_mov_b32_e32 v45, v2
	v_mov_b32_e32 v46, v2
	v_mov_b32_e32 v47, v2
	v_mov_b32_e32 v48, v2
	v_mov_b32_e32 v49, v2
	v_mov_b32_e32 v50, v2
	v_mov_b32_e32 v51, v2
	v_mov_b32_e32 v52, v2
	v_mov_b32_e32 v53, v2
	v_mov_b32_e32 v54, v2
	v_mov_b32_e32 v55, v2
	v_mov_b32_e32 v56, v2
	v_mov_b32_e32 v57, v2
	v_mov_b32_e32 v58, v2
	v_mov_b32_e32 v59, v2
	v_mov_b32_e32 v60, v2
	v_mov_b32_e32 v61, v2
	v_mov_b32_e32 v62, v2
	v_mov_b32_e32 v63, v2
	v_mov_b32_e32 v64, v2
	v_mov_b32_e32 v65, v2
	s_mov_b64 s[18:19], 0x6ae4100
	s_mov_b64 s[40:41], 0x6aec100
	s_mov_b32 s36, 0
	s_mov_b32 s0, 0
	s_branch .Lein_head

; template <int EPI, int ROWS>
; __device__ __forceinline__ void epi_process(const Params& p, int l, int m0, int n0, const float* Cs, int tid) {
;     ...
;         if (tid < 2 * ROWS) {
;             const int sl = tid / ROWS, rl = tid - sl * ROWS;
;             const int row = m0 + rl;
;             float v[64];
; #pragma unroll
;             for (int c = 0; c < 64; ++c) v[c] = Cs[rl * 129 + sl * 64 + c];
;             const int b = row / TOK, t = row - b * TOK;
;             epi_seg<EPI>(p, l, row, b, t, (n0 >> 6) + sl, v);
; template <int EPI>
; __device__ __forceinline__ void gemm_tile(const Params& p, int l, const u16* __restrict__ A, int lda, const u16* __restrict__ Bt, int K, int m0, int n0, unsigned char* smem) {
;     ...
;     for (int kt = 0; kt < nk; ++kt) {
;         if (((kt + 1) & 3) == wid && kt + 1 < nk) asm volatile("s_waitcnt vmcnt(0)" ::: "memory");
;         __builtin_amdgcn_s_barrier();
;         asm volatile("" ::: "memory");
;         if ((kt & 3) == wid && kt + 4 < nk) G_TILE(kt + 4, stn);
;         const int so = st * 16384;
;         bf16x8 af[4], bv[4];
; #pragma unroll
;         for (int i = 0; i < 4; ++i) af[i] = *(const bf16x8*)(fa + so + i * 1024);
; #pragma unroll
;         for (int j = 0; j < 4; ++j) bv[j] = *(const bf16x8*)(fb + so + j * 1024);
;         __builtin_amdgcn_s_setprio(1);
; #pragma unroll
;         for (int i = 0; i < 4; ++i)
; #pragma unroll
;             for (int j = 0; j < 4; ++j) acc[i][j] = __builtin_amdgcn_mfma_f32_16x16x32_bf16(af[i], bv[j], acc[i][j], 0, 0, 0);
;         __builtin_amdgcn_s_setprio(0);
;         st = (st == 4) ? 0 : st + 1;
;         stn = (stn == 4) ? 0 : stn + 1;
;     }
;     __syncthreads();
;     float* Cs = (float*)smem;
;     constexpr int CS = (EPI == EPI_FFN1 || EPI == EPI_Y) ? 132 : 129;
; #pragma unroll
;     for (int i = 0; i < 4; ++i)
; #pragma unroll
;         for (int j = 0; j < 4; ++j)
; #pragma unroll
;             for (int r = 0; r < 4; ++r) Cs[(wr * 64 + i * 16 + fq * 4 + r) * CS + wc * 64 + j * 16 + fr] = acc[i][j][r];
;     __syncthreads();
;     epi_process<EPI, 128>(p, l, m0, n0, Cs, tid);
.LBB0_481:
	s_waitcnt vmcnt(0)
	s_barrier
	ds_read_b128 v[68:71], v75 offset:16384
	ds_read_b128 v[76:79], v75 offset:17408
	ds_read_b128 v[80:83], v75 offset:18432
	ds_read_b128 v[84:87], v75 offset:19456
	ds_read_b128 v[88:91], v74 offset:24576
	ds_read_b128 v[92:95], v74 offset:25600
	ds_read_b128 v[96:99], v74 offset:26624
	ds_read_b128 v[100:103], v74 offset:27648
	s_setprio 1
	s_waitcnt lgkmcnt(0)
	v_mfma_f32_16x16x32_bf16 v[62:65], v[68:71], v[88:91], v[62:65]
	v_mfma_f32_16x16x32_bf16 v[58:61], v[68:71], v[92:95], v[58:61]
	v_mfma_f32_16x16x32_bf16 v[54:57], v[68:71], v[96:99], v[54:57]
	v_mfma_f32_16x16x32_bf16 v[50:53], v[68:71], v[100:103], v[50:53]
	v_mfma_f32_16x16x32_bf16 v[46:49], v[76:79], v[88:91], v[46:49]
	v_mfma_f32_16x16x32_bf16 v[42:45], v[76:79], v[92:95], v[42:45]
	v_mfma_f32_16x16x32_bf16 v[38:41], v[76:79], v[96:99], v[38:41]
	v_mfma_f32_16x16x32_bf16 v[34:37], v[76:79], v[100:103], v[34:37]
	v_mfma_f32_16x16x32_bf16 v[30:33], v[80:83], v[88:91], v[30:33]
	v_mfma_f32_16x16x32_bf16 v[26:29], v[80:83], v[92:95], v[26:29]
	v_mfma_f32_16x16x32_bf16 v[22:25], v[80:83], v[96:99], v[22:25]
	v_mfma_f32_16x16x32_bf16 v[18:21], v[80:83], v[100:103], v[18:21]
	v_mfma_f32_16x16x32_bf16 v[14:17], v[84:87], v[88:91], v[14:17]
	v_mfma_f32_16x16x32_bf16 v[10:13], v[84:87], v[92:95], v[10:13]
	v_mfma_f32_16x16x32_bf16 v[6:9], v[84:87], v[96:99], v[6:9]
	v_mfma_f32_16x16x32_bf16 v[2:5], v[84:87], v[100:103], v[2:5]
	s_setprio 0
	v_lshrrev_b32_e32 v66, 2, v110
	v_and_b32_e32 v66, 12, v66
	v_lshl_or_b32 v66, v73, 6, v66
	s_movk_i32 s0, 0x204
	v_lshl_add_u32 v67, v67, 8, 0
	v_lshlrev_b32_e32 v68, 2, v72
	v_mul_lo_u32 v66, v66, s0
	v_add3_u32 v66, v67, v68, v66
	s_waitcnt vmcnt(0)
	s_barrier
	ds_write2_b32 v66, v62, v58 offset1:16
	ds_write2_b32 v66, v63, v59 offset0:129 offset1:145
	v_add_u32_e32 v58, 0x400, v66
	ds_write2_b32 v58, v64, v60 offset0:2 offset1:18
	ds_write2_b32 v58, v65, v61 offset0:131 offset1:147
	ds_write2_b32 v66, v54, v50 offset0:32 offset1:48
	ds_write2_b32 v66, v55, v51 offset0:161 offset1:177
	ds_write2_b32 v58, v56, v52 offset0:34 offset1:50
	ds_write2_b32 v58, v57, v53 offset0:163 offset1:179
	v_add_u32_e32 v50, 0x2000, v66
	ds_write2_b32 v50, v46, v42 offset0:16 offset1:32
	ds_write2_b32 v50, v47, v43 offset0:145 offset1:161
	v_add_u32_e32 v42, 0x2400, v66
	ds_write2_b32 v42, v48, v44 offset0:18 offset1:34
	ds_write2_b32 v42, v49, v45 offset0:147 offset1:163
	ds_write2_b32 v50, v38, v34 offset0:48 offset1:64
	ds_write2_b32 v50, v39, v35 offset0:177 offset1:193
	ds_write2_b32 v42, v40, v36 offset0:50 offset1:66
	ds_write2_b32 v42, v41, v37 offset0:179 offset1:195
	v_add_u32_e32 v34, 0x4000, v66
	ds_write2_b32 v34, v30, v26 offset0:32 offset1:48
	ds_write2_b32 v34, v31, v27 offset0:161 offset1:177
	v_add_u32_e32 v26, 0x4400, v66
	ds_write2_b32 v26, v32, v28 offset0:34 offset1:50
	ds_write2_b32 v26, v33, v29 offset0:163 offset1:179
	ds_write2_b32 v34, v22, v18 offset0:64 offset1:80
	ds_write2_b32 v34, v23, v19 offset0:193 offset1:209
	ds_write2_b32 v26, v24, v20 offset0:66 offset1:82
	ds_write2_b32 v26, v25, v21 offset0:195 offset1:211
	v_add_u32_e32 v18, 0x6000, v66
	ds_write2_b32 v18, v14, v10 offset0:48 offset1:64
	ds_write2_b32 v18, v15, v11 offset0:177 offset1:193
	v_add_u32_e32 v10, 0x6400, v66
	v_cmp_gt_i32_e32 vcc, s51, v110
	ds_write2_b32 v10, v16, v12 offset0:50 offset1:66
	ds_write2_b32 v10, v17, v13 offset0:179 offset1:195
	ds_write2_b32 v18, v6, v2 offset0:80 offset1:96
	ds_write2_b32 v18, v7, v3 offset0:209 offset1:225
	ds_write2_b32 v10, v8, v4 offset0:82 offset1:98
	ds_write2_b32 v10, v9, v5 offset0:211 offset1:227
	s_waitcnt lgkmcnt(0)
	s_barrier
	s_and_saveexec_b64 s[0:1], vcc
	s_cbranch_execz .LBB0_468
	v_ashrrev_i32_e32 v2, 31, v110
	v_lshrrev_b32_e32 v2, 25, v2
	v_add_u32_e32 v2, v110, v2
	v_ashrrev_i32_e32 v3, 7, v2
	v_and_b32_e32 v2, 0xffffff80, v2
	v_sub_u32_e32 v2, v110, v2
	s_movk_i32 s17, 0x204
	v_mul_lo_u32 v4, v2, s17
	v_lshlrev_b32_e32 v5, 8, v3
	v_add3_u32 v4, 0, v4, v5
	ds_read2_b32 v[106:107], v4 offset1:1
	ds_read2_b32 v[104:105], v4 offset0:2 offset1:3
	ds_read2_b32 v[102:103], v4 offset0:4 offset1:5
	ds_read2_b32 v[100:101], v4 offset0:6 offset1:7
	ds_read2_b32 v[98:99], v4 offset0:8 offset1:9
	ds_read2_b32 v[96:97], v4 offset0:10 offset1:11
	ds_read2_b32 v[84:85], v4 offset0:12 offset1:13
	ds_read2_b32 v[82:83], v4 offset0:14 offset1:15
	ds_read2_b32 v[56:57], v4 offset0:16 offset1:17
	ds_read2_b32 v[54:55], v4 offset0:18 offset1:19
	ds_read2_b32 v[52:53], v4 offset0:20 offset1:21
	ds_read2_b32 v[50:51], v4 offset0:22 offset1:23
	ds_read2_b32 v[48:49], v4 offset0:24 offset1:25
	ds_read2_b32 v[46:47], v4 offset0:26 offset1:27
	ds_read2_b32 v[44:45], v4 offset0:28 offset1:29
	ds_read2_b32 v[42:43], v4 offset0:30 offset1:31
	ds_read2_b32 v[94:95], v4 offset0:32 offset1:33
	ds_read2_b32 v[90:91], v4 offset0:34 offset1:35
	ds_read2_b32 v[88:89], v4 offset0:36 offset1:37
	ds_read2_b32 v[86:87], v4 offset0:38 offset1:39
	ds_read2_b32 v[80:81], v4 offset0:40 offset1:41
	ds_read2_b32 v[78:79], v4 offset0:42 offset1:43
	ds_read2_b32 v[76:77], v4 offset0:44 offset1:45
	ds_read2_b32 v[74:75], v4 offset0:46 offset1:47
	ds_read2_b32 v[72:73], v4 offset0:48 offset1:49
	ds_read2_b32 v[70:71], v4 offset0:50 offset1:51
	ds_read2_b32 v[68:69], v4 offset0:52 offset1:53
	ds_read2_b32 v[66:67], v4 offset0:54 offset1:55
	ds_read2_b32 v[64:65], v4 offset0:56 offset1:57
	ds_read2_b32 v[62:63], v4 offset0:58 offset1:59
	ds_read2_b32 v[60:61], v4 offset0:60 offset1:61
	ds_read2_b32 v[58:59], v4 offset0:62 offset1:63
	v_lshl_add_u32 v108, s50, 7, v2
	s_mov_b32 s17, 0x38e38e39
	v_mul_hi_i32 v2, v108, s17
	v_lshrrev_b32_e32 v4, 31, v2
	v_ashrrev_i32_e32 v2, 9, v2
	v_add_u32_e32 v109, v2, v4
	s_movk_i32 s17, 0xf700
	v_lshl_add_u32 v92, s59, 1, v3
	v_mad_i32_i24 v93, v109, s17, v108
	v_cmp_lt_i32_e32 vcc, 7, v92
	s_and_saveexec_b64 s[28:29], vcc
	s_xor_b64 s[36:37], exec, s[28:29]
	s_cbranch_execz .LBB0_506
; template <int O>
; __device__ __forceinline__ void rope32(float (&v)[64], const float* R8, int t) {
;     if (t < CTX) return;
;     const int pp = t - CTX, pr = pp >> 6, pc = pp & 63;
;     const float2* tr = (const float2*)R8 + pr * 8;
;     const float2* tc = (const float2*)R8 + pc * 8;
; #pragma unroll
;     for (int i = 0; i < 8; ++i) {
;         const float2 cs = tr[i];
;         const float a = v[O + i], bb = v[O + i + 8];
;         v[O + i] = a * cs.x - bb * cs.y; v[O + i + 8] = bb * cs.x + a * cs.y;
;     }
; #pragma unroll
;     for (int i = 0; i < 8; ++i) {
;         const float2 cs = tc[i];
;         const float a = v[O + 16 + i], bb = v[O + 24 + i];
;         v[O + 16 + i] = a * cs.x - bb * cs.y; v[O + 24 + i] = bb * cs.x + a * cs.y;
;     }
; }
; template <int EPI>
; __device__ __forceinline__ void epi_seg(const Params& p, int l, int row, int b, int t, int seg, float (&v)[64]) {
;     ...
;         else if (seg == 18) { rope32<0>(v, R8, t); store_row<32>((u16*)(ws + P_KPE) + (size_t)row * 32, v); }
	v_cmp_lt_u32_e32 vcc, 9, v92
	s_and_saveexec_b64 s[28:29], vcc
	s_xor_b64 s[28:29], exec, s[28:29]
	s_cbranch_execz .LBB0_501
	v_cmp_lt_u32_e32 vcc, 11, v92
	s_and_saveexec_b64 s[30:31], vcc
	s_xor_b64 s[38:39], exec, s[30:31]
	s_cbranch_execz .LBB0_498
	v_cmp_lt_u32_e32 vcc, 15, v92
	s_and_saveexec_b64 s[30:31], vcc
	s_xor_b64 s[30:31], exec, s[30:31]
	s_cbranch_execz .LBB0_495
	v_cmp_lt_u32_e32 vcc, 17, v92
	s_and_saveexec_b64 s[40:41], vcc
	s_xor_b64 s[40:41], exec, s[40:41]
	s_cbranch_execz .LBB0_492
	v_cmp_eq_u32_e32 vcc, 18, v92
	s_and_saveexec_b64 s[42:43], vcc
	s_cbranch_execz .LBB0_491
	s_movk_i32 s17, 0xff
	v_cmp_lt_i32_e32 vcc, s17, v93
	s_and_saveexec_b64 s[44:45], vcc
	s_cbranch_execz .LBB0_490
	v_add_u32_e32 v0, 0xffffff00, v93
	v_readlane_b32 s18, v251, 63
	v_and_b32_e32 v0, 0xffffffc0, v0
	v_readlane_b32 s19, v250, 0
	s_nop 4
	global_load_dwordx4 v[2:5], v0, s[18:19]
	global_load_dwordx4 v[6:9], v0, s[18:19] offset:16
	global_load_dwordx4 v[10:13], v0, s[18:19] offset:32
	global_load_dwordx4 v[14:17], v0, s[18:19] offset:48
	v_lshlrev_b32_e32 v0, 6, v110
	v_and_b32_e32 v0, 0xfc0, v0
	global_load_dwordx4 v[18:21], v0, s[18:19]
	global_load_dwordx4 v[22:25], v0, s[18:19] offset:16
	global_load_dwordx4 v[26:29], v0, s[18:19] offset:48
	global_load_dwordx4 v[30:33], v0, s[18:19] offset:32
	s_waitcnt vmcnt(7) lgkmcnt(14)
	v_mul_f32_e32 v34, v106, v2
	s_waitcnt vmcnt(6)
	v_mul_f32_e32 v40, v104, v6
	s_waitcnt lgkmcnt(0)
	v_mul_f32_e32 v58, v96, v7
	v_mul_f32_e32 v6, v96, v6
	v_mul_f32_e32 v60, v104, v7
	v_mov_b32_e32 v96, v105
	v_mov_b32_e32 v104, v97
	v_pk_mul_f32 v[92:93], v[96:97], v[8:9]
	v_pk_mul_f32 v[8:9], v[104:105], v[8:9]
	v_mul_f32_e32 v36, v98, v3
	v_mul_f32_e32 v2, v98, v2
	v_mul_f32_e32 v38, v106, v3
	v_mov_b32_e32 v98, v107
	v_mov_b32_e32 v106, v99
	s_waitcnt vmcnt(5)
	v_mul_f32_e32 v62, v102, v10
	v_mul_f32_e32 v64, v84, v11
	v_mul_f32_e32 v10, v84, v10
	v_mul_f32_e32 v66, v102, v11
	v_mov_b32_e32 v84, v103
	v_mov_b32_e32 v102, v85
	v_mov_b32_e32 v7, v8
	v_mov_b32_e32 v61, v9
	s_waitcnt vmcnt(2)
	v_mul_f32_e32 v80, v54, v22
	v_mul_f32_e32 v88, v54, v23
	v_pk_mul_f32 v[90:91], v[98:99], v[4:5]
	v_pk_mul_f32 v[4:5], v[106:107], v[4:5]
	v_pk_mul_f32 v[84:85], v[84:85], v[12:13]
	v_pk_mul_f32 v[12:13], v[102:103], v[12:13]
	v_pk_add_f32 v[96:97], v[6:7], v[60:61]
	v_mov_b32_e32 v54, v47
	s_waitcnt vmcnt(0)
	v_mul_f32_e32 v6, v44, v31
	v_mul_f32_e32 v8, v44, v30
	v_mov_b32_e32 v44, v53
	v_mov_b32_e32 v3, v4
	v_mov_b32_e32 v39, v5
	v_mov_b32_e32 v11, v12
	v_mov_b32_e32 v67, v13
	v_pk_mul_f32 v[4:5], v[54:55], v[24:25]
	v_pk_mul_f32 v[12:13], v[44:45], v[32:33]
	v_mul_f32_e32 v86, v46, v23
	v_mov_b32_e32 v63, v84
	v_mov_b32_e32 v65, v85
	v_pk_add_f32 v[84:85], v[10:11], v[66:67]
	v_mov_b32_e32 v23, v4
	v_mov_b32_e32 v89, v5
	v_mul_f32_e32 v4, v52, v30
	v_mul_f32_e32 v10, v52, v31
	v_mov_b32_e32 v5, v12
	v_mov_b32_e32 v7, v13
	v_mov_b32_e32 v52, v45
	v_mul_f32_e32 v68, v100, v14
	v_mul_f32_e32 v70, v82, v15
	v_mul_f32_e32 v14, v82, v14
	v_mul_f32_e32 v72, v100, v15
	v_mov_b32_e32 v82, v101
	v_mov_b32_e32 v100, v83
	v_pk_add_f32 v[4:5], v[4:5], v[6:7] neg_lo:[0,1] neg_hi:[0,1]
	v_pk_mul_f32 v[6:7], v[52:53], v[32:33]
	v_pk_mul_f32 v[82:83], v[82:83], v[16:17]
	v_pk_mul_f32 v[16:17], v[100:101], v[16:17]
	v_mov_b32_e32 v9, v6
	v_mov_b32_e32 v11, v7
	v_mov_b32_e32 v15, v16
	v_mov_b32_e32 v73, v17
	v_pk_add_f32 v[44:45], v[8:9], v[10:11]
	v_mul_f32_e32 v8, v42, v27
	v_mul_f32_e32 v10, v42, v26
	v_mov_b32_e32 v42, v51
	v_mul_f32_e32 v22, v46, v22
	v_mov_b32_e32 v69, v82
	v_mov_b32_e32 v71, v83
	v_pk_add_f32 v[82:83], v[14:15], v[72:73]
	v_mov_b32_e32 v46, v55
	v_pk_mul_f32 v[14:15], v[42:43], v[28:29]
	v_mul_f32_e32 v74, v56, v18
	v_mul_f32_e32 v76, v48, v19
	v_mul_f32_e32 v18, v48, v18
	v_mul_f32_e32 v78, v56, v19
	v_mov_b32_e32 v48, v57
	v_mov_b32_e32 v56, v49
	v_pk_add_f32 v[98:99], v[2:3], v[38:39]
	v_pk_mul_f32 v[2:3], v[46:47], v[24:25]
	v_mul_f32_e32 v6, v50, v26
	v_mul_f32_e32 v12, v50, v27
	v_mov_b32_e32 v7, v14
	v_mov_b32_e32 v9, v15
	v_mov_b32_e32 v50, v43
	v_pk_mul_f32 v[48:49], v[48:49], v[20:21]
	v_pk_mul_f32 v[20:21], v[56:57], v[20:21]
	v_mov_b32_e32 v81, v2
	v_mov_b32_e32 v87, v3
	v_pk_add_f32 v[6:7], v[6:7], v[8:9] neg_lo:[0,1] neg_hi:[0,1]
	v_pk_mul_f32 v[8:9], v[50:51], v[28:29]
	v_mov_b32_e32 v35, v90
	v_mov_b32_e32 v37, v91
	v_mov_b32_e32 v41, v92
	v_mov_b32_e32 v59, v93
	v_mov_b32_e32 v75, v48
	v_mov_b32_e32 v77, v49
	v_mov_b32_e32 v19, v20
	v_mov_b32_e32 v79, v21
	v_pk_add_f32 v[2:3], v[80:81], v[86:87] neg_lo:[0,1] neg_hi:[0,1]
	v_mov_b32_e32 v11, v8
	v_mov_b32_e32 v13, v9
	v_pk_add_f32 v[106:107], v[34:35], v[36:37] neg_lo:[0,1] neg_hi:[0,1]
	v_pk_add_f32 v[104:105], v[40:41], v[58:59] neg_lo:[0,1] neg_hi:[0,1]
	v_pk_add_f32 v[102:103], v[62:63], v[64:65] neg_lo:[0,1] neg_hi:[0,1]
	v_pk_add_f32 v[100:101], v[68:69], v[70:71] neg_lo:[0,1] neg_hi:[0,1]
	v_pk_add_f32 v[56:57], v[74:75], v[76:77] neg_lo:[0,1] neg_hi:[0,1]
	v_pk_add_f32 v[48:49], v[18:19], v[78:79]
	v_pk_add_f32 v[46:47], v[22:23], v[88:89]
	v_pk_add_f32 v[42:43], v[10:11], v[12:13]
	v_mov_b64_e32 v[50:51], v[6:7]
	v_mov_b64_e32 v[52:53], v[4:5]
	v_mov_b64_e32 v[54:55], v[2:3]

; __device__ __forceinline__ int opaque_tid() { int t = threadIdx.x; asm volatile("" : "+v"(t)); return t; }
; #define G3_TILE(kt_, st_) do { const size_t ko_ = (size_t)(kt_) * 1024; unsigned char* d_ = smem + (st_) * 20480; \
;         _Pragma("unroll") for (int s_ = 0; s_ < 12; ++s_) GLDS16(Abase + (size_t)s_ * ksub + ko_ + voff, d_ + s_ * 1024); \
;         _Pragma("unroll") for (int s_ = 0; s_ < 8; ++s_) GLDS16(Bbase + (size_t)s_ * ksub + ko_ + voff, d_ + 12288 + s_ * 1024); } while (0)
; template <int EPI>
; __device__ __forceinline__ void gemm_tile3(const Params& p, int l, const u16* __restrict__ A, int lda, const u16* __restrict__ Bt, int K, int m0, int n0, unsigned char* smem) {
;     const int tid = opaque_tid(), lane = tid & 63, wid = tid >> 6, wr = wid >> 1, wc = wid & 1, fr = lane & 15, fq = lane >> 4;
;     f32x4 acc[6][4];
; #pragma unroll
;     for (int i = 0; i < 6; ++i)
; #pragma unroll
;         for (int j = 0; j < 4; ++j) acc[i][j] = (f32x4){0.f, 0.f, 0.f, 0.f};
;     const unsigned voff = (unsigned)(lane * 16);
;     const size_t ksub = (size_t)(K >> 5) * 1024;
;     const unsigned char* Abase = (const unsigned char*)A + (size_t)(m0 >> 4) * ksub;
;     const unsigned char* Bbase = (const unsigned char*)Bt + (size_t)(n0 >> 4) * ksub;
;     (void)lda;
;     ...
;     const int nk = K >> 5;
;     if (wid < 3) G3_TILE(wid, wid);
;     const unsigned char* fa = smem + (wr * 6) * 1024 + fr * 64 + fq * 16;
;     const unsigned char* fb = smem + 12288 + (wc * 4) * 1024 + fr * 64 + fq * 16;
;     int st = 0, stn = 3;
;     if (wid == 0) asm volatile("s_waitcnt vmcnt(0)" ::: "memory");
;     asm volatile("s_waitcnt lgkmcnt(0)" ::: "memory");
;     __builtin_amdgcn_s_barrier();
;     asm volatile("" ::: "memory");
.LBB0_895:
	s_mulk_i32 s1, 0xfea0
	s_add_i32 s1, s1, s0
	s_lshl_b32 s0, s1, 4
	s_and_b32 s49, s0, 0xffffff80
	s_mul_i32 s23, s16, 0xc0
	v_mov_b32_e32 v106, v197
	s_ashr_i32 s28, s49, 4
	s_lshr_b32 s84, s23, 4
	v_ashrrev_i32_e32 v98, 6, v106
	v_lshlrev_b32_e32 v0, 4, v106
	s_ashr_i32 s29, s28, 31
	v_and_b32_e32 v0, 0x3f0, v0
	s_lshl_b64 s[0:1], s[84:85], 15
	s_lshl_b64 s[28:29], s[28:29], 15
	v_and_b32_e32 v252, 32, v106
	v_xor_b32_e32 v252, v252, v0
	v_add_u32_e32 v253, 0x8000, v252
	v_add_u32_e32 v254, 0x10000, v252
	v_readfirstlane_b32 s16, v98
	s_add_u32 s0, s76, s0
	s_addc_u32 s1, s77, s1
	s_add_u32 s30, s39, s28
	s_addc_u32 s31, s40, s29
	s_mul_i32 s17, s16, 0x18000
	s_add_u32 s28, s0, s17
	s_addc_u32 s29, s1, 0
	s_lshl_b32 s17, s16, 16
	s_add_u32 s30, s30, s17
	s_addc_u32 s31, s31, 0
	s_mul_i32 s54, s16, 0xc00
	s_lshl_b32 s0, s16, 11
	s_addk_i32 s0, 0x3000
	s_mov_b32 s51, 0
.Lf1_pro:
	s_add_i32 s17, s51, s54
	s_add_i32 s18, s51, s0
	s_mov_b32 m0, s17
	s_add_i32 s17, s17, 0x400
	global_load_lds_dwordx4 v252, s[28:29]
	s_mov_b32 m0, s17
	s_add_i32 s17, s17, 0x400
	global_load_lds_dwordx4 v253, s[28:29]
	s_mov_b32 m0, s17
	s_nop 0
	global_load_lds_dwordx4 v254, s[28:29]
	s_mov_b32 m0, s18
	s_add_i32 s18, s18, 0x400
	global_load_lds_dwordx4 v252, s[30:31]
	s_mov_b32 m0, s18
	s_add_u32 s28, s28, 0x400
	global_load_lds_dwordx4 v253, s[30:31]
	s_addc_u32 s29, s29, 0
	s_add_u32 s30, s30, 0x400
	s_addc_u32 s31, s31, 0
	s_add_i32 s51, s51, 0x5000
	s_cmp_lg_u32 s51, 0xf000
	s_cbranch_scc1 .Lf1_pro
	v_ashrrev_i32_e32 v99, 7, v106
	s_movk_i32 s17, 0x1800
	v_and_b32_e32 v103, 15, v106
	v_mul_lo_u32 v2, v99, s17
	v_and_b32_e32 v107, 1, v98
	v_lshlrev_b32_e32 v102, 6, v103
	v_and_b32_e32 v3, 48, v106
	v_and_b32_e32 v4, 8, v106
	v_lshlrev_b32_e32 v4, 2, v4
	v_xor_b32_e32 v3, v3, v4
	v_add3_u32 v108, v2, v102, v3
	v_lshlrev_b32_e32 v2, 12, v107
	v_add3_u32 v109, v2, v102, v3
	s_waitcnt lgkmcnt(0)
	v_mov_b32_e32 v2, 0
	v_mov_b32_e32 v3, v2
	v_mov_b32_e32 v4, v2
	v_mov_b32_e32 v5, v2
	v_mov_b32_e32 v6, v2
	v_mov_b32_e32 v7, v2
	v_mov_b32_e32 v8, v2
	v_mov_b32_e32 v9, v2
	v_mov_b32_e32 v10, v2
	v_mov_b32_e32 v11, v2
	v_mov_b32_e32 v12, v2
	v_mov_b32_e32 v13, v2
	v_mov_b32_e32 v14, v2
	v_mov_b32_e32 v15, v2
	v_mov_b32_e32 v16, v2
	v_mov_b32_e32 v17, v2
	v_mov_b32_e32 v22, v2
	v_mov_b32_e32 v23, v2
	v_mov_b32_e32 v24, v2
	v_mov_b32_e32 v25, v2
	v_mov_b32_e32 v18, v2
	v_mov_b32_e32 v19, v2
	v_mov_b32_e32 v20, v2
	v_mov_b32_e32 v21, v2
	v_mov_b32_e32 v26, v2
	v_mov_b32_e32 v27, v2
	v_mov_b32_e32 v28, v2
	v_mov_b32_e32 v29, v2
	v_mov_b32_e32 v30, v2
	v_mov_b32_e32 v31, v2
	v_mov_b32_e32 v32, v2
	v_mov_b32_e32 v33, v2
	v_mov_b32_e32 v38, v2
	v_mov_b32_e32 v39, v2
	v_mov_b32_e32 v40, v2
	v_mov_b32_e32 v41, v2
	v_mov_b32_e32 v34, v2
	v_mov_b32_e32 v35, v2
	v_mov_b32_e32 v36, v2
	v_mov_b32_e32 v37, v2
	v_mov_b32_e32 v42, v2
	v_mov_b32_e32 v43, v2
	v_mov_b32_e32 v44, v2
	v_mov_b32_e32 v45, v2
	v_mov_b32_e32 v46, v2
	v_mov_b32_e32 v47, v2
	v_mov_b32_e32 v48, v2
	v_mov_b32_e32 v49, v2
	v_mov_b32_e32 v54, v2
	v_mov_b32_e32 v55, v2
	v_mov_b32_e32 v56, v2
	v_mov_b32_e32 v57, v2
	v_mov_b32_e32 v50, v2
	v_mov_b32_e32 v51, v2
	v_mov_b32_e32 v52, v2
	v_mov_b32_e32 v53, v2
	v_mov_b32_e32 v58, v2
	v_mov_b32_e32 v59, v2
	v_mov_b32_e32 v60, v2
	v_mov_b32_e32 v61, v2
	v_mov_b32_e32 v62, v2
	v_mov_b32_e32 v63, v2
	v_mov_b32_e32 v64, v2
	v_mov_b32_e32 v65, v2
	v_mov_b32_e32 v70, v2
	v_mov_b32_e32 v71, v2
	v_mov_b32_e32 v72, v2
	v_mov_b32_e32 v73, v2
	v_mov_b32_e32 v66, v2
	v_mov_b32_e32 v67, v2
	v_mov_b32_e32 v68, v2
	v_mov_b32_e32 v69, v2
	v_mov_b32_e32 v74, v2
	v_mov_b32_e32 v75, v2
	v_mov_b32_e32 v76, v2
	v_mov_b32_e32 v77, v2
	v_mov_b32_e32 v78, v2
	v_mov_b32_e32 v79, v2
	v_mov_b32_e32 v80, v2
	v_mov_b32_e32 v81, v2
	v_mov_b32_e32 v82, v2
	v_mov_b32_e32 v83, v2
	v_mov_b32_e32 v84, v2
	v_mov_b32_e32 v85, v2
	v_mov_b32_e32 v86, v2
	v_mov_b32_e32 v87, v2
	v_mov_b32_e32 v88, v2
	v_mov_b32_e32 v89, v2
	v_mov_b32_e32 v90, v2
	v_mov_b32_e32 v91, v2
	v_mov_b32_e32 v92, v2
	v_mov_b32_e32 v93, v2
	v_mov_b32_e32 v94, v2
	v_mov_b32_e32 v95, v2
	v_mov_b32_e32 v96, v2
	v_mov_b32_e32 v97, v2
	s_mov_b32 s16, 0
	s_mov_b32 s50, 0
	s_branch .Lf1_head

; __device__ __forceinline__ int opaque_tid() { int t = threadIdx.x; asm volatile("" : "+v"(t)); return t; }
; #define G3_TILE(kt_, st_) do { const size_t ko_ = (size_t)(kt_) * 1024; unsigned char* d_ = smem + (st_) * 20480; \
;         _Pragma("unroll") for (int s_ = 0; s_ < 12; ++s_) GLDS16(Abase + (size_t)s_ * ksub + ko_ + voff, d_ + s_ * 1024); \
;         _Pragma("unroll") for (int s_ = 0; s_ < 8; ++s_) GLDS16(Bbase + (size_t)s_ * ksub + ko_ + voff, d_ + 12288 + s_ * 1024); } while (0)
; template <int EPI>
; __device__ __forceinline__ void gemm_tile3(const Params& p, int l, const u16* __restrict__ A, int lda, const u16* __restrict__ Bt, int K, int m0, int n0, unsigned char* smem) {
;     const int tid = opaque_tid(), lane = tid & 63, wid = tid >> 6, wr = wid >> 1, wc = wid & 1, fr = lane & 15, fq = lane >> 4;
;     f32x4 acc[6][4];
; #pragma unroll
;     for (int i = 0; i < 6; ++i)
; #pragma unroll
;         for (int j = 0; j < 4; ++j) acc[i][j] = (f32x4){0.f, 0.f, 0.f, 0.f};
;     const unsigned voff = (unsigned)(lane * 16);
;     const size_t ksub = (size_t)(K >> 5) * 1024;
;     const unsigned char* Abase = (const unsigned char*)A + (size_t)(m0 >> 4) * ksub;
;     const unsigned char* Bbase = (const unsigned char*)Bt + (size_t)(n0 >> 4) * ksub;
;     (void)lda;
;     ...
;     const int nk = K >> 5;
;     if (wid < 3) G3_TILE(wid, wid);
;     const unsigned char* fa = smem + (wr * 6) * 1024 + fr * 64 + fq * 16;
;     const unsigned char* fb = smem + 12288 + (wc * 4) * 1024 + fr * 64 + fq * 16;
;     int st = 0, stn = 3;
;     if (wid == 0) asm volatile("s_waitcnt vmcnt(0)" ::: "memory");
;     asm volatile("s_waitcnt lgkmcnt(0)" ::: "memory");
;     __builtin_amdgcn_s_barrier();
;     asm volatile("" ::: "memory");
;     for (int kt = 0; kt < nk; ++kt) {
;         if (((kt + 1) & 3) == wid && kt + 1 < nk) asm volatile("s_waitcnt vmcnt(0)" ::: "memory");
;         __builtin_amdgcn_s_barrier();
;         asm volatile("" ::: "memory");
;         if (((kt + 3) & 3) == wid && kt + 3 < nk) G3_TILE(kt + 3, stn);
.LBB0_959:
	s_lshl_b32 s23, s23, 7
	s_lshl_b32 s0, s0, 4
	s_sub_i32 s0, s0, s23
	s_mulk_i32 s1, 0xc0
	s_and_b32 s0, s0, 0xffffff80
	v_mov_b32_e32 v104, v197
	s_lshr_b32 s41, s1, 4
	v_ashrrev_i32_e32 v98, 6, v104
	v_lshlrev_b32_e32 v0, 4, v104
	s_ashr_i32 s31, s0, 4
	v_and_b32_e32 v0, 0x3f0, v0
	s_mul_hi_u32 s30, s41, 0x16000
	s_mul_i32 s41, s41, 0x16000
	s_mul_hi_i32 s23, s31, 0x16000
	s_mul_i32 s31, s31, 0x16000
	v_and_b32_e32 v252, 32, v104
	v_xor_b32_e32 v252, v252, v0
	v_add_u32_e32 v253, 0x16000, v252
	v_add_u32_e32 v254, 0x2c000, v252
	v_readfirstlane_b32 s49, v98
	s_add_u32 s28, s26, s41
	s_addc_u32 s29, s27, s30
	s_add_u32 s30, s16, s31
	s_addc_u32 s31, s39, s23
	s_mul_i32 s17, s49, 0x42000
	s_add_u32 s28, s28, s17
	s_addc_u32 s29, s29, 0
	s_mul_i32 s17, s49, 0x2c000
	s_add_u32 s30, s30, s17
	s_addc_u32 s31, s31, 0
	s_mul_i32 s54, s49, 0xc00
	s_lshl_b32 s55, s49, 11
	s_addk_i32 s55, 0x3000
	s_mov_b32 s23, 0
.Lf2_pro:
	s_add_i32 s17, s23, s54
	s_add_i32 s18, s23, s55
	s_mov_b32 m0, s17
	s_add_i32 s17, s17, 0x400
	global_load_lds_dwordx4 v252, s[28:29]
	s_mov_b32 m0, s17
	s_add_i32 s17, s17, 0x400
	global_load_lds_dwordx4 v253, s[28:29]
	s_mov_b32 m0, s17
	s_nop 0
	global_load_lds_dwordx4 v254, s[28:29]
	s_mov_b32 m0, s18
	s_add_i32 s18, s18, 0x400
	global_load_lds_dwordx4 v252, s[30:31]
	s_mov_b32 m0, s18
	s_add_u32 s28, s28, 0x400
	global_load_lds_dwordx4 v253, s[30:31]
	s_addc_u32 s29, s29, 0
	s_add_u32 s30, s30, 0x400
	s_addc_u32 s31, s31, 0
	s_add_i32 s23, s23, 0x5000
	s_cmp_lg_u32 s23, 0xf000
	s_cbranch_scc1 .Lf2_pro
	v_ashrrev_i32_e32 v105, 7, v104
	s_movk_i32 s17, 0x1800
	v_and_b32_e32 v106, 15, v104
	v_mul_lo_u32 v2, v105, s17
	v_and_b32_e32 v99, 1, v98
	v_lshlrev_b32_e32 v3, 6, v106
	v_and_b32_e32 v4, 48, v104
	v_and_b32_e32 v5, 8, v104
	v_lshlrev_b32_e32 v5, 2, v5
	v_xor_b32_e32 v4, v4, v5
	v_add3_u32 v107, v2, v3, v4
	v_lshlrev_b32_e32 v2, 12, v99
	v_add3_u32 v108, v2, v3, v4
	s_waitcnt lgkmcnt(0)
	v_mov_b32_e32 v2, 0
	v_mov_b32_e32 v3, v2
	v_mov_b32_e32 v4, v2
	v_mov_b32_e32 v5, v2
	v_mov_b32_e32 v6, v2
	v_mov_b32_e32 v7, v2
	v_mov_b32_e32 v8, v2
	v_mov_b32_e32 v9, v2
	v_mov_b32_e32 v10, v2
	v_mov_b32_e32 v11, v2
	v_mov_b32_e32 v12, v2
	v_mov_b32_e32 v13, v2
	v_mov_b32_e32 v14, v2
	v_mov_b32_e32 v15, v2
	v_mov_b32_e32 v16, v2
	v_mov_b32_e32 v17, v2
	v_mov_b32_e32 v18, v2
	v_mov_b32_e32 v19, v2
	v_mov_b32_e32 v20, v2
	v_mov_b32_e32 v21, v2
	v_mov_b32_e32 v22, v2
	v_mov_b32_e32 v23, v2
	v_mov_b32_e32 v24, v2
	v_mov_b32_e32 v25, v2
	v_mov_b32_e32 v26, v2
	v_mov_b32_e32 v27, v2
	v_mov_b32_e32 v28, v2
	v_mov_b32_e32 v29, v2
	v_mov_b32_e32 v30, v2
	v_mov_b32_e32 v31, v2
	v_mov_b32_e32 v32, v2
	v_mov_b32_e32 v33, v2
	v_mov_b32_e32 v34, v2
	v_mov_b32_e32 v35, v2
	v_mov_b32_e32 v36, v2
	v_mov_b32_e32 v37, v2
	v_mov_b32_e32 v38, v2
	v_mov_b32_e32 v39, v2
	v_mov_b32_e32 v40, v2
	v_mov_b32_e32 v41, v2
	v_mov_b32_e32 v42, v2
	v_mov_b32_e32 v43, v2
	v_mov_b32_e32 v44, v2
	v_mov_b32_e32 v45, v2
	v_mov_b32_e32 v46, v2
	v_mov_b32_e32 v47, v2
	v_mov_b32_e32 v48, v2
	v_mov_b32_e32 v49, v2
	v_mov_b32_e32 v50, v2
	v_mov_b32_e32 v51, v2
	v_mov_b32_e32 v52, v2
	v_mov_b32_e32 v53, v2
	v_mov_b32_e32 v54, v2
	v_mov_b32_e32 v55, v2
	v_mov_b32_e32 v56, v2
	v_mov_b32_e32 v57, v2
	v_mov_b32_e32 v58, v2
	v_mov_b32_e32 v59, v2
	v_mov_b32_e32 v60, v2
	v_mov_b32_e32 v61, v2
	v_mov_b32_e32 v62, v2
	v_mov_b32_e32 v63, v2
	v_mov_b32_e32 v64, v2
	v_mov_b32_e32 v65, v2
	v_mov_b32_e32 v66, v2
	v_mov_b32_e32 v67, v2
	v_mov_b32_e32 v68, v2
	v_mov_b32_e32 v69, v2
	v_mov_b32_e32 v70, v2
	v_mov_b32_e32 v71, v2
	v_mov_b32_e32 v72, v2
	v_mov_b32_e32 v73, v2
	v_mov_b32_e32 v74, v2
	v_mov_b32_e32 v75, v2
	v_mov_b32_e32 v76, v2
	v_mov_b32_e32 v77, v2
	v_mov_b32_e32 v78, v2
	v_mov_b32_e32 v79, v2
	v_mov_b32_e32 v80, v2
	v_mov_b32_e32 v81, v2
	v_mov_b32_e32 v82, v2
	v_mov_b32_e32 v83, v2
	v_mov_b32_e32 v84, v2
	v_mov_b32_e32 v85, v2
	v_mov_b32_e32 v86, v2
	v_mov_b32_e32 v87, v2
	v_mov_b32_e32 v88, v2
	v_mov_b32_e32 v89, v2
	v_mov_b32_e32 v90, v2
	v_mov_b32_e32 v91, v2
	v_mov_b32_e32 v92, v2
	v_mov_b32_e32 v93, v2
	v_mov_b32_e32 v94, v2
	v_mov_b32_e32 v95, v2
	v_mov_b32_e32 v96, v2
	v_mov_b32_e32 v97, v2
	s_mov_b32 s50, 0
	s_mov_b32 s41, 0
	s_branch .Lf2_head
.Lf2_wt:
	s_cmp_eq_u32 s50, 86
	s_cbranch_scc0 .Lf2_w0
	s_waitcnt vmcnt(5)
	s_branch .Lf2_bar

; template <int EPI>
; __device__ __forceinline__ void gemm_tile3(const Params& p, int l, const u16* __restrict__ A, int lda, const u16* __restrict__ Bt, int K, int m0, int n0, unsigned char* smem) {
;     ...
;     for (int kt = 0; kt < nk; ++kt) {
;         if (((kt + 1) & 3) == wid && kt + 1 < nk) asm volatile("s_waitcnt vmcnt(0)" ::: "memory");
;         __builtin_amdgcn_s_barrier();
;         asm volatile("" ::: "memory");
;         if (((kt + 3) & 3) == wid && kt + 3 < nk) G3_TILE(kt + 3, stn);
;         const int so = st * 20480;
;         bf16x8 af[6], bv[4];
;         {
;             typedef __attribute__((address_space(3))) unsigned char lds_u8;
;             const unsigned la = (unsigned)(uintptr_t)(lds_u8*)(fa + so);
;             const unsigned lb = (unsigned)(uintptr_t)(lds_u8*)(fb + so);
;     ...
;             DSR128(bv[0], lb, 0); DSR128(bv[1], lb, 1024); DSR128(bv[2], lb, 2048); DSR128(bv[3], lb, 3072);
;             DSR128(af[0], la, 0); DSR128(af[1], la, 1024); DSR128(af[2], la, 2048); DSR128(af[3], la, 3072); DSR128(af[4], la, 4096); DSR128(af[5], la, 5120);
;         }
;         __builtin_amdgcn_sched_barrier(0);
;         asm volatile("s_waitcnt lgkmcnt(5)" : "+v"(bv[0]), "+v"(bv[1]), "+v"(bv[2]), "+v"(bv[3]), "+v"(af[0]));
;         __builtin_amdgcn_sched_barrier(0);
; #pragma unroll
;         for (int j = 0; j < 4; ++j) acc[0][j] = __builtin_amdgcn_mfma_f32_16x16x32_bf16(bv[j], af[0], acc[0][j], 0, 0, 0);
;         __builtin_amdgcn_sched_barrier(0);
;         asm volatile("s_waitcnt lgkmcnt(4)" : "+v"(af[1]));
;         __builtin_amdgcn_sched_barrier(0);
; #pragma unroll
;         for (int j = 0; j < 4; ++j) acc[1][j] = __builtin_amdgcn_mfma_f32_16x16x32_bf16(bv[j], af[1], acc[1][j], 0, 0, 0);
;         __builtin_amdgcn_sched_barrier(0);
;         asm volatile("s_waitcnt lgkmcnt(3)" : "+v"(af[2]));
;         __builtin_amdgcn_sched_barrier(0);
; #pragma unroll
;         for (int j = 0; j < 4; ++j) acc[2][j] = __builtin_amdgcn_mfma_f32_16x16x32_bf16(bv[j], af[2], acc[2][j], 0, 0, 0);
;         __builtin_amdgcn_sched_barrier(0);
;         asm volatile("s_waitcnt lgkmcnt(2)" : "+v"(af[3]));
;         __builtin_amdgcn_sched_barrier(0);
; #pragma unroll
;         for (int j = 0; j < 4; ++j) acc[3][j] = __builtin_amdgcn_mfma_f32_16x16x32_bf16(bv[j], af[3], acc[3][j], 0, 0, 0);
;         __builtin_amdgcn_sched_barrier(0);
.Lf2_head:
	s_cmp_lt_u32 s50, 86
	s_cbranch_scc0 .Lf2_wt
	s_waitcnt vmcnt(10)
.Lf2_bar:
	s_barrier
	v_add_u32_e32 v109, s41, v108
	v_add_u32_e32 v0, s41, v107
	v_add_u32_e32 v109, 0x3000, v109
	ds_read_b128 v[110:113], v109 offset:0
	ds_read_b128 v[114:117], v109 offset:1024
	ds_read_b128 v[118:121], v109 offset:2048
	ds_read_b128 v[122:125], v109 offset:3072
	ds_read_b128 v[126:129], v0 offset:0
	ds_read_b128 v[130:133], v0 offset:1024
	ds_read_b128 v[134:137], v0 offset:2048
	ds_read_b128 v[138:141], v0 offset:3072
	ds_read_b128 v[142:145], v0 offset:4096
	ds_read_b128 v[146:149], v0 offset:5120
	s_cmp_lt_u32 s50, 85
	s_cbranch_scc0 .Lf2_mm
	s_add_i32 s17, s23, s54
	s_add_i32 s18, s23, s55
	s_mov_b32 m0, s17
	s_add_i32 s17, s17, 0x400
	global_load_lds_dwordx4 v252, s[28:29]
	s_mov_b32 m0, s17
	s_add_i32 s17, s17, 0x400
	global_load_lds_dwordx4 v253, s[28:29]
	s_mov_b32 m0, s17
	s_nop 0
	global_load_lds_dwordx4 v254, s[28:29]
	s_mov_b32 m0, s18
	s_add_i32 s18, s18, 0x400
	global_load_lds_dwordx4 v252, s[30:31]
	s_mov_b32 m0, s18
	s_add_u32 s28, s28, 0x400
	global_load_lds_dwordx4 v253, s[30:31]
	s_addc_u32 s29, s29, 0
	s_add_u32 s30, s30, 0x400
	s_addc_u32 s31, s31, 0
	s_add_i32 s23, s23, 0x5000
	s_cmp_eq_u32 s23, 0x14000
	s_cselect_b32 s23, 0, s23
.Lf2_mm:
	s_waitcnt lgkmcnt(5)
	s_nop 0
	v_mfma_f32_16x16x32_bf16 v[94:97], v[110:113], v[126:129], v[94:97]
	v_mfma_f32_16x16x32_bf16 v[90:93], v[114:117], v[126:129], v[90:93]
	v_mfma_f32_16x16x32_bf16 v[86:89], v[118:121], v[126:129], v[86:89]
	v_mfma_f32_16x16x32_bf16 v[82:85], v[122:125], v[126:129], v[82:85]
	s_waitcnt lgkmcnt(4)
	s_nop 0
	v_mfma_f32_16x16x32_bf16 v[78:81], v[110:113], v[130:133], v[78:81]
	v_mfma_f32_16x16x32_bf16 v[74:77], v[114:117], v[130:133], v[74:77]
	v_mfma_f32_16x16x32_bf16 v[70:73], v[118:121], v[130:133], v[70:73]
	v_mfma_f32_16x16x32_bf16 v[66:69], v[122:125], v[130:133], v[66:69]
	s_waitcnt lgkmcnt(3)
	s_nop 0
	v_mfma_f32_16x16x32_bf16 v[62:65], v[110:113], v[134:137], v[62:65]
	v_mfma_f32_16x16x32_bf16 v[58:61], v[114:117], v[134:137], v[58:61]
	v_mfma_f32_16x16x32_bf16 v[54:57], v[118:121], v[134:137], v[54:57]
	v_mfma_f32_16x16x32_bf16 v[50:53], v[122:125], v[134:137], v[50:53]
	s_waitcnt lgkmcnt(2)
	s_nop 0
	v_mfma_f32_16x16x32_bf16 v[46:49], v[110:113], v[138:141], v[46:49]
	v_mfma_f32_16x16x32_bf16 v[42:45], v[114:117], v[138:141], v[42:45]
	v_mfma_f32_16x16x32_bf16 v[38:41], v[118:121], v[138:141], v[38:41]
	v_mfma_f32_16x16x32_bf16 v[34:37], v[122:125], v[138:141], v[34:37]
	s_waitcnt lgkmcnt(1)
	s_nop 0
	v_mfma_f32_16x16x32_bf16 v[30:33], v[110:113], v[142:145], v[30:33]
	v_mfma_f32_16x16x32_bf16 v[26:29], v[114:117], v[142:145], v[26:29]
	v_mfma_f32_16x16x32_bf16 v[22:25], v[118:121], v[142:145], v[22:25]
	v_mfma_f32_16x16x32_bf16 v[18:21], v[122:125], v[142:145], v[18:21]
	s_waitcnt lgkmcnt(0)
	s_add_i32 s41, s41, 0x5000
	s_add_i32 s50, s50, 1
	v_mfma_f32_16x16x32_bf16 v[14:17], v[110:113], v[146:149], v[14:17]
	s_cmp_eq_u32 s41, 0x14000
	s_cselect_b32 s41, 0, s41
	v_mfma_f32_16x16x32_bf16 v[10:13], v[114:117], v[146:149], v[10:13]
	s_cmp_lg_u32 s50, 88
	v_mfma_f32_16x16x32_bf16 v[6:9], v[118:121], v[146:149], v[6:9]
	v_mfma_f32_16x16x32_bf16 v[2:5], v[122:125], v[146:149], v[2:5]
	s_cbranch_scc1 .Lf2_head
	s_branch .LBB0_956
